# GEMM mainloops: redundant s_waitcnt lgkmcnt(0) after the sub-phase barrier removed (24 sites; the wait before the barrier already covers the fragment reads)
# baseline (speedup 1.0000x reference)
; #define PG8_STAGE(bufoff, gbase, voff) do { _Pragma("unroll") for (int _i = 0; _i < 2; ++_i) \
;         __builtin_amdgcn_global_load_lds((const unsigned*)((const char*)(gbase) + (voff)[_i]), (LAS unsigned*)(lds + (bufoff) + ldsw + _i * 8192), 16, 0, 0); } while (0)
; #define PG8_LDA(dst, b, h) do { _Pragma("unroll") for (int m = 0; m < 4; ++m) _Pragma("unroll") for (int k = 0; k < 2; ++k) dst[m][k] = *(const LAS bf16x8*)(lds + PG8_SA(b, h) + aoff + m * 2048 + k * 1024); } while (0)
; #define PG8_LDB(dst, b, h) do { _Pragma("unroll") for (int n = 0; n < 2; ++n) _Pragma("unroll") for (int k = 0; k < 2; ++k) dst[n][k] = *(const LAS bf16x8*)(lds + PG8_SB(b, h) + boff + n * 2048 + k * 1024); } while (0)
; #define PG8_MMA(ai, bj, At, Bt) do { __builtin_amdgcn_s_setprio(1); _Pragma("unroll") for (int m = 0; m < 4; ++m) _Pragma("unroll") for (int n = 0; n < 2; ++n) _Pragma("unroll") for (int k = 0; k < 2; ++k) \
;         acc[ai][bj][m][n] = __builtin_amdgcn_mfma_f32_16x16x32_bf16(Bt[n][k], At[m][k], acc[ai][bj][m][n], 0, 0, 0); __builtin_amdgcn_s_setprio(0); } while (0)
; #define PG8_WAIT_V(n) asm volatile("s_waitcnt vmcnt(" #n ")" ::: "memory")
; #define PG8_WAIT_L(n) asm volatile("s_waitcnt lgkmcnt(" #n ")" ::: "memory")
; #define PG8_BAR __builtin_amdgcn_s_barrier()
; #define PG8_SCHED __builtin_amdgcn_sched_barrier(0)
; template <class Epi>
; __device__ __forceinline__ void gemm_phase(LAS unsigned char* lds, const Gemm g, const StaticOrder& S, const Epi& E) {
;     ...
;             PG8_LDB(B0, 0, 0); PG8_LDB(B1, 0, 1); PG8_SCHED; PG8_LDA(At, 0, 0); PG8_STAGE(PG8_SA(1, 1), a1 + hstep, voffA);
;             PG8_WAIT_V(8); PG8_WAIT_L(0); PG8_BAR; PG8_MMA(0, 0, At, B0); PG8_MMA(0, 1, At, B1); PG8_BAR; PG8_SCHED;
;             PG8_LDA(At, 0, 1); PG8_STAGE(PG8_SB(0, 0), b2, voffB); PG8_STAGE(PG8_SB(0, 1), b2 + hstep, voffB); PG8_STAGE(PG8_SA(0, 0), a2, voffA);
;             PG8_WAIT_V(8); PG8_WAIT_L(0); PG8_BAR; PG8_MMA(1, 0, At, B0); PG8_MMA(1, 1, At, B1); PG8_BAR; PG8_SCHED;
.LBB0_74:
	ds_read_b128 v[146:149], v153
	ds_read_b128 v[156:159], v153 offset:1024
	ds_read_b128 v[160:163], v153 offset:2048
	ds_read_b128 v[164:167], v153 offset:3072
	ds_read_b128 v[168:171], v154
	ds_read_b128 v[172:175], v154 offset:1024
	ds_read_b128 v[176:179], v154 offset:2048
	ds_read_b128 v[180:183], v154 offset:3072
	s_add_u32 s36, s34, 0xfffc0080
	s_addc_u32 s37, s35, -1
	s_cmp_eq_u32 s61, 12
	s_cselect_b32 s39, s21, s37
	s_cselect_b32 s38, s57, s36
	s_cselect_b32 s37, s19, s60
	s_cselect_b32 s36, s58, s59
	v_lshl_add_u64 v[216:217], s[34:35], 0, v[138:139]
	s_add_i32 m0, s31, 0xc000
	ds_read_b128 v[184:187], v155
	ds_read_b128 v[188:191], v155 offset:1024
	ds_read_b128 v[192:195], v155 offset:2048
	ds_read_b128 v[196:199], v155 offset:3072
	ds_read_b128 v[200:203], v155 offset:4096
	ds_read_b128 v[204:207], v155 offset:5120
	ds_read_b128 v[208:211], v155 offset:6144
	ds_read_b128 v[212:215], v155 offset:7168
	global_load_lds_dwordx4 v[216:217], off
	v_lshl_add_u64 v[216:217], s[34:35], 0, v[140:141]
	s_add_i32 m0, s31, 0xe000
	s_nop 0
	global_load_lds_dwordx4 v[216:217], off
	s_waitcnt vmcnt(8)
	s_waitcnt lgkmcnt(0)
	s_barrier
	s_setprio 1
	v_mfma_f32_16x16x32_bf16 v[126:129], v[146:149], v[184:187], v[126:129]
	v_mfma_f32_16x16x32_bf16 v[118:121], v[160:163], v[184:187], v[118:121]
	v_mfma_f32_16x16x32_bf16 v[110:113], v[146:149], v[192:195], v[110:113]
	v_mfma_f32_16x16x32_bf16 v[102:105], v[160:163], v[192:195], v[102:105]
	v_mfma_f32_16x16x32_bf16 v[94:97], v[146:149], v[200:203], v[94:97]
	v_mfma_f32_16x16x32_bf16 v[86:89], v[160:163], v[200:203], v[86:89]
	v_mfma_f32_16x16x32_bf16 v[78:81], v[146:149], v[208:211], v[78:81]
	v_mfma_f32_16x16x32_bf16 v[70:73], v[160:163], v[208:211], v[70:73]
	v_mfma_f32_16x16x32_bf16 v[126:129], v[156:159], v[188:191], v[126:129]
	v_mfma_f32_16x16x32_bf16 v[118:121], v[164:167], v[188:191], v[118:121]
	v_mfma_f32_16x16x32_bf16 v[110:113], v[156:159], v[196:199], v[110:113]
	v_mfma_f32_16x16x32_bf16 v[102:105], v[164:167], v[196:199], v[102:105]
	v_mfma_f32_16x16x32_bf16 v[94:97], v[156:159], v[204:207], v[94:97]
	v_mfma_f32_16x16x32_bf16 v[86:89], v[164:167], v[204:207], v[86:89]
	v_mfma_f32_16x16x32_bf16 v[78:81], v[156:159], v[212:215], v[78:81]
	v_mfma_f32_16x16x32_bf16 v[70:73], v[164:167], v[212:215], v[70:73]
	s_setprio 0
	s_setprio 1
	v_mfma_f32_16x16x32_bf16 v[122:125], v[168:171], v[184:187], v[122:125]
	v_mfma_f32_16x16x32_bf16 v[114:117], v[176:179], v[184:187], v[114:117]
	v_mfma_f32_16x16x32_bf16 v[106:109], v[168:171], v[192:195], v[106:109]
	v_mfma_f32_16x16x32_bf16 v[98:101], v[176:179], v[192:195], v[98:101]
	v_mfma_f32_16x16x32_bf16 v[90:93], v[168:171], v[200:203], v[90:93]
	v_mfma_f32_16x16x32_bf16 v[82:85], v[176:179], v[200:203], v[82:85]
	v_mfma_f32_16x16x32_bf16 v[74:77], v[168:171], v[208:211], v[74:77]
	v_mfma_f32_16x16x32_bf16 v[66:69], v[176:179], v[208:211], v[66:69]
	v_mfma_f32_16x16x32_bf16 v[122:125], v[172:175], v[188:191], v[122:125]
	v_mfma_f32_16x16x32_bf16 v[114:117], v[180:183], v[188:191], v[114:117]
	v_mfma_f32_16x16x32_bf16 v[106:109], v[172:175], v[196:199], v[106:109]
	v_mfma_f32_16x16x32_bf16 v[98:101], v[180:183], v[196:199], v[98:101]
	v_mfma_f32_16x16x32_bf16 v[90:93], v[172:175], v[204:207], v[90:93]
	v_mfma_f32_16x16x32_bf16 v[82:85], v[180:183], v[204:207], v[82:85]
	v_mfma_f32_16x16x32_bf16 v[74:77], v[172:175], v[212:215], v[74:77]
	v_mfma_f32_16x16x32_bf16 v[66:69], v[180:183], v[212:215], v[66:69]
	s_setprio 0
	s_barrier
	s_add_i32 s62, s53, s43
	v_lshl_add_u64 v[216:217], s[36:37], 0, v[134:135]
	s_mov_b32 m0, s62
	ds_read_b128 v[184:187], v155 offset:16384
	ds_read_b128 v[188:191], v155 offset:17408
	ds_read_b128 v[192:195], v155 offset:18432
	ds_read_b128 v[196:199], v155 offset:19456
	ds_read_b128 v[200:203], v155 offset:20480
	ds_read_b128 v[204:207], v155 offset:21504
	ds_read_b128 v[208:211], v155 offset:22528
	ds_read_b128 v[212:215], v155 offset:23552
	global_load_lds_dwordx4 v[216:217], off
	s_add_i32 m0, s62, 0x2000
	s_add_u32 s62, s36, 0x40000
	v_lshl_add_u64 v[218:219], s[36:37], 0, v[130:131]
	s_addc_u32 s63, s37, 0
	s_add_i32 s64, s54, s43
	global_load_lds_dwordx4 v[218:219], off
	v_lshl_add_u64 v[220:221], s[62:63], 0, v[134:135]
	s_mov_b32 m0, s64
	v_lshl_add_u64 v[222:223], s[38:39], 0, v[132:133]
	global_load_lds_dwordx4 v[220:221], off
	v_lshl_add_u64 v[220:221], s[62:63], 0, v[130:131]
	s_add_i32 m0, s64, 0x2000
	s_nop 0
	global_load_lds_dwordx4 v[220:221], off
	v_lshl_add_u64 v[220:221], s[38:39], 0, v[136:137]
	s_mov_b32 m0, s31
	s_nop 0
	global_load_lds_dwordx4 v[220:221], off
	s_mov_b32 m0, s46
	s_nop 0
	global_load_lds_dwordx4 v[222:223], off
	s_waitcnt vmcnt(8)
	s_waitcnt lgkmcnt(0)
	s_barrier
; #define PG8_STAGE(bufoff, gbase, voff) do { _Pragma("unroll") for (int _i = 0; _i < 2; ++_i) \
;         __builtin_amdgcn_global_load_lds((const unsigned*)((const char*)(gbase) + (voff)[_i]), (LAS unsigned*)(lds + (bufoff) + ldsw + _i * 8192), 16, 0, 0); } while (0)
; #define PG8_LDA(dst, b, h) do { _Pragma("unroll") for (int m = 0; m < 4; ++m) _Pragma("unroll") for (int k = 0; k < 2; ++k) dst[m][k] = *(const LAS bf16x8*)(lds + PG8_SA(b, h) + aoff + m * 2048 + k * 1024); } while (0)
; #define PG8_LDB(dst, b, h) do { _Pragma("unroll") for (int n = 0; n < 2; ++n) _Pragma("unroll") for (int k = 0; k < 2; ++k) dst[n][k] = *(const LAS bf16x8*)(lds + PG8_SB(b, h) + boff + n * 2048 + k * 1024); } while (0)
; #define PG8_MMA(ai, bj, At, Bt) do { __builtin_amdgcn_s_setprio(1); _Pragma("unroll") for (int m = 0; m < 4; ++m) _Pragma("unroll") for (int n = 0; n < 2; ++n) _Pragma("unroll") for (int k = 0; k < 2; ++k) \
;         acc[ai][bj][m][n] = __builtin_amdgcn_mfma_f32_16x16x32_bf16(Bt[n][k], At[m][k], acc[ai][bj][m][n], 0, 0, 0); __builtin_amdgcn_s_setprio(0); } while (0)
; #define PG8_WAIT_V(n) asm volatile("s_waitcnt vmcnt(" #n ")" ::: "memory")
; #define PG8_WAIT_L(n) asm volatile("s_waitcnt lgkmcnt(" #n ")" ::: "memory")
; #define PG8_BAR __builtin_amdgcn_s_barrier()
; #define PG8_SCHED __builtin_amdgcn_sched_barrier(0)
; template <class Epi>
; __device__ __forceinline__ void gemm_phase(LAS unsigned char* lds, const Gemm g, const StaticOrder& S, const Epi& E) {
;     ...
;             PG8_WAIT_V(8); PG8_WAIT_L(0); PG8_BAR; PG8_MMA(1, 0, At, B0); PG8_MMA(1, 1, At, B1); PG8_BAR; PG8_SCHED;
;             PG8_LDB(B0, 1, 0); PG8_LDB(B1, 1, 1); PG8_SCHED; PG8_LDA(At, 1, 0); PG8_STAGE(PG8_SA(0, 1), a2 + hstep, voffA);
;             PG8_WAIT_V(8); PG8_WAIT_L(0); PG8_BAR; PG8_MMA(0, 0, At, B0); PG8_MMA(0, 1, At, B1); PG8_BAR; PG8_SCHED;
;             PG8_LDA(At, 1, 1); PG8_STAGE(PG8_SB(1, 0), b3, voffB); PG8_STAGE(PG8_SB(1, 1), b3 + hstep, voffB); PG8_STAGE(PG8_SA(1, 0), a3, voffA);
	s_setprio 1
	v_mfma_f32_16x16x32_bf16 v[62:65], v[146:149], v[184:187], v[62:65]
	v_mfma_f32_16x16x32_bf16 v[54:57], v[160:163], v[184:187], v[54:57]
	v_mfma_f32_16x16x32_bf16 v[46:49], v[146:149], v[192:195], v[46:49]
	v_mfma_f32_16x16x32_bf16 v[38:41], v[160:163], v[192:195], v[38:41]
	v_mfma_f32_16x16x32_bf16 v[30:33], v[146:149], v[200:203], v[30:33]
	v_mfma_f32_16x16x32_bf16 v[22:25], v[160:163], v[200:203], v[22:25]
	v_mfma_f32_16x16x32_bf16 v[14:17], v[146:149], v[208:211], v[14:17]
	v_mfma_f32_16x16x32_bf16 v[6:9], v[160:163], v[208:211], v[6:9]
	v_mfma_f32_16x16x32_bf16 v[62:65], v[156:159], v[188:191], v[62:65]
	v_mfma_f32_16x16x32_bf16 v[54:57], v[164:167], v[188:191], v[54:57]
	v_mfma_f32_16x16x32_bf16 v[46:49], v[156:159], v[196:199], v[46:49]
	v_mfma_f32_16x16x32_bf16 v[38:41], v[164:167], v[196:199], v[38:41]
	v_mfma_f32_16x16x32_bf16 v[30:33], v[156:159], v[204:207], v[30:33]
	v_mfma_f32_16x16x32_bf16 v[22:25], v[164:167], v[204:207], v[22:25]
	v_mfma_f32_16x16x32_bf16 v[14:17], v[156:159], v[212:215], v[14:17]
	v_mfma_f32_16x16x32_bf16 v[6:9], v[164:167], v[212:215], v[6:9]
	s_setprio 0
	s_setprio 1
	v_mfma_f32_16x16x32_bf16 v[58:61], v[168:171], v[184:187], v[58:61]
	v_mfma_f32_16x16x32_bf16 v[50:53], v[176:179], v[184:187], v[50:53]
	v_mfma_f32_16x16x32_bf16 v[42:45], v[168:171], v[192:195], v[42:45]
	v_mfma_f32_16x16x32_bf16 v[34:37], v[176:179], v[192:195], v[34:37]
	v_mfma_f32_16x16x32_bf16 v[26:29], v[168:171], v[200:203], v[26:29]
	v_mfma_f32_16x16x32_bf16 v[18:21], v[176:179], v[200:203], v[18:21]
	v_mfma_f32_16x16x32_bf16 v[10:13], v[168:171], v[208:211], v[10:13]
	v_mfma_f32_16x16x32_bf16 v[2:5], v[176:179], v[208:211], v[2:5]
	v_mfma_f32_16x16x32_bf16 v[58:61], v[172:175], v[188:191], v[58:61]
	v_mfma_f32_16x16x32_bf16 v[50:53], v[180:183], v[188:191], v[50:53]
	v_mfma_f32_16x16x32_bf16 v[42:45], v[172:175], v[196:199], v[42:45]
	v_mfma_f32_16x16x32_bf16 v[34:37], v[180:183], v[196:199], v[34:37]
	v_mfma_f32_16x16x32_bf16 v[26:29], v[172:175], v[204:207], v[26:29]
	v_mfma_f32_16x16x32_bf16 v[18:21], v[180:183], v[204:207], v[18:21]
	v_mfma_f32_16x16x32_bf16 v[10:13], v[172:175], v[212:215], v[10:13]
	v_mfma_f32_16x16x32_bf16 v[2:5], v[180:183], v[212:215], v[2:5]
	s_setprio 0
	s_barrier
	s_add_i32 s62, 0, 0x18000
	s_add_i32 s63, 0, 0x1c000
	v_add_u32_e32 v164, s62, v151
	v_add_u32_e32 v180, s63, v151
	ds_read_b128 v[146:149], v164
	ds_read_b128 v[156:159], v164 offset:1024
	ds_read_b128 v[160:163], v164 offset:2048
	ds_read_b128 v[164:167], v164 offset:3072
	ds_read_b128 v[168:171], v180
	ds_read_b128 v[172:175], v180 offset:1024
	ds_read_b128 v[176:179], v180 offset:2048
	ds_read_b128 v[180:183], v180 offset:3072
	s_add_u32 s38, s38, 0x40000
	s_addc_u32 s39, s39, 0
	s_mov_b32 m0, s47
	v_lshl_add_u64 v[224:225], s[38:39], 0, v[136:137]
	ds_read_b128 v[184:187], v155 offset:32768
	ds_read_b128 v[188:191], v155 offset:33792
	ds_read_b128 v[192:195], v155 offset:34816
	ds_read_b128 v[196:199], v155 offset:35840
	ds_read_b128 v[200:203], v155 offset:36864
	ds_read_b128 v[204:207], v155 offset:37888
	ds_read_b128 v[208:211], v155 offset:38912
	ds_read_b128 v[212:215], v155 offset:39936
	global_load_lds_dwordx4 v[224:225], off
	v_lshl_add_u64 v[224:225], s[38:39], 0, v[132:133]
	s_mov_b32 m0, s48
	s_nop 0
	global_load_lds_dwordx4 v[224:225], off
	s_waitcnt vmcnt(8)
	s_waitcnt lgkmcnt(0)
	s_barrier
	s_setprio 1
	v_mfma_f32_16x16x32_bf16 v[126:129], v[146:149], v[184:187], v[126:129]
	v_mfma_f32_16x16x32_bf16 v[118:121], v[160:163], v[184:187], v[118:121]
	v_mfma_f32_16x16x32_bf16 v[110:113], v[146:149], v[192:195], v[110:113]
	v_mfma_f32_16x16x32_bf16 v[102:105], v[160:163], v[192:195], v[102:105]
	v_mfma_f32_16x16x32_bf16 v[94:97], v[146:149], v[200:203], v[94:97]
	v_mfma_f32_16x16x32_bf16 v[86:89], v[160:163], v[200:203], v[86:89]
	v_mfma_f32_16x16x32_bf16 v[78:81], v[146:149], v[208:211], v[78:81]
	v_mfma_f32_16x16x32_bf16 v[70:73], v[160:163], v[208:211], v[70:73]
	v_mfma_f32_16x16x32_bf16 v[126:129], v[156:159], v[188:191], v[126:129]
	v_mfma_f32_16x16x32_bf16 v[118:121], v[164:167], v[188:191], v[118:121]
	v_mfma_f32_16x16x32_bf16 v[110:113], v[156:159], v[196:199], v[110:113]
	v_mfma_f32_16x16x32_bf16 v[102:105], v[164:167], v[196:199], v[102:105]
	v_mfma_f32_16x16x32_bf16 v[94:97], v[156:159], v[204:207], v[94:97]
	v_mfma_f32_16x16x32_bf16 v[86:89], v[164:167], v[204:207], v[86:89]
	v_mfma_f32_16x16x32_bf16 v[78:81], v[156:159], v[212:215], v[78:81]
	v_mfma_f32_16x16x32_bf16 v[70:73], v[164:167], v[212:215], v[70:73]
	s_setprio 0
	s_setprio 1
	v_mfma_f32_16x16x32_bf16 v[122:125], v[168:171], v[184:187], v[122:125]
	v_mfma_f32_16x16x32_bf16 v[114:117], v[176:179], v[184:187], v[114:117]
	v_mfma_f32_16x16x32_bf16 v[106:109], v[168:171], v[192:195], v[106:109]
	v_mfma_f32_16x16x32_bf16 v[98:101], v[176:179], v[192:195], v[98:101]
	v_mfma_f32_16x16x32_bf16 v[90:93], v[168:171], v[200:203], v[90:93]
	v_mfma_f32_16x16x32_bf16 v[82:85], v[176:179], v[200:203], v[82:85]
	v_mfma_f32_16x16x32_bf16 v[74:77], v[168:171], v[208:211], v[74:77]
	v_mfma_f32_16x16x32_bf16 v[66:69], v[176:179], v[208:211], v[66:69]
	v_mfma_f32_16x16x32_bf16 v[122:125], v[172:175], v[188:191], v[122:125]
	v_mfma_f32_16x16x32_bf16 v[114:117], v[180:183], v[188:191], v[114:117]
	v_mfma_f32_16x16x32_bf16 v[106:109], v[172:175], v[196:199], v[106:109]
	v_mfma_f32_16x16x32_bf16 v[98:101], v[180:183], v[196:199], v[98:101]
	v_mfma_f32_16x16x32_bf16 v[90:93], v[172:175], v[204:207], v[90:93]
	v_mfma_f32_16x16x32_bf16 v[82:85], v[180:183], v[204:207], v[82:85]
	v_mfma_f32_16x16x32_bf16 v[74:77], v[172:175], v[212:215], v[74:77]
	v_mfma_f32_16x16x32_bf16 v[66:69], v[180:183], v[212:215], v[66:69]
	s_setprio 0
	s_barrier
; #define PG8_STAGE(bufoff, gbase, voff) do { _Pragma("unroll") for (int _i = 0; _i < 2; ++_i) \
;         __builtin_amdgcn_global_load_lds((const unsigned*)((const char*)(gbase) + (voff)[_i]), (LAS unsigned*)(lds + (bufoff) + ldsw + _i * 8192), 16, 0, 0); } while (0)
; #define PG8_LDA(dst, b, h) do { _Pragma("unroll") for (int m = 0; m < 4; ++m) _Pragma("unroll") for (int k = 0; k < 2; ++k) dst[m][k] = *(const LAS bf16x8*)(lds + PG8_SA(b, h) + aoff + m * 2048 + k * 1024); } while (0)
; #define PG8_MMA(ai, bj, At, Bt) do { __builtin_amdgcn_s_setprio(1); _Pragma("unroll") for (int m = 0; m < 4; ++m) _Pragma("unroll") for (int n = 0; n < 2; ++n) _Pragma("unroll") for (int k = 0; k < 2; ++k) \
;         acc[ai][bj][m][n] = __builtin_amdgcn_mfma_f32_16x16x32_bf16(Bt[n][k], At[m][k], acc[ai][bj][m][n], 0, 0, 0); __builtin_amdgcn_s_setprio(0); } while (0)
; #define PG8_WAIT_V(n) asm volatile("s_waitcnt vmcnt(" #n ")" ::: "memory")
; #define PG8_WAIT_L(n) asm volatile("s_waitcnt lgkmcnt(" #n ")" ::: "memory")
; #define PG8_BAR __builtin_amdgcn_s_barrier()
; #define PG8_SCHED __builtin_amdgcn_sched_barrier(0)
; template <class Epi>
; __device__ __forceinline__ void gemm_phase(LAS unsigned char* lds, const Gemm g, const StaticOrder& S, const Epi& E) {
;     ...
;             PG8_LDA(At, 1, 1); PG8_STAGE(PG8_SB(1, 0), b3, voffB); PG8_STAGE(PG8_SB(1, 1), b3 + hstep, voffB); PG8_STAGE(PG8_SA(1, 0), a3, voffA);
;             PG8_WAIT_V(8); PG8_WAIT_L(0); PG8_BAR; PG8_MMA(1, 0, At, B0); PG8_MMA(1, 1, At, B1); PG8_BAR; PG8_SCHED;
;         }
	s_add_i32 s38, s62, s43
	v_lshl_add_u64 v[216:217], v[216:217], 0, s[8:9]
	s_mov_b32 m0, s38
	ds_read_b128 v[184:187], v155 offset:49152
	ds_read_b128 v[188:191], v155 offset:50176
	ds_read_b128 v[192:195], v155 offset:51200
	ds_read_b128 v[196:199], v155 offset:52224
	ds_read_b128 v[200:203], v155 offset:53248
	ds_read_b128 v[204:207], v155 offset:54272
	ds_read_b128 v[208:211], v155 offset:55296
	ds_read_b128 v[212:215], v155 offset:56320
	global_load_lds_dwordx4 v[216:217], off
	s_add_i32 m0, s38, 0x2000
	s_add_u32 s36, s36, 0x40080
	v_lshl_add_u64 v[216:217], v[218:219], 0, s[8:9]
	s_addc_u32 s37, s37, 0
	s_add_i32 s38, s63, s43
	global_load_lds_dwordx4 v[216:217], off
	v_lshl_add_u64 v[216:217], s[36:37], 0, v[134:135]
	s_mov_b32 m0, s38
	s_nop 0
	global_load_lds_dwordx4 v[216:217], off
	v_lshl_add_u64 v[216:217], s[36:37], 0, v[130:131]
	s_add_i32 m0, s38, 0x2000
	s_nop 0
	global_load_lds_dwordx4 v[216:217], off
	v_lshl_add_u64 v[216:217], v[220:221], 0, s[8:9]
	s_mov_b32 m0, s50
	s_nop 0
	global_load_lds_dwordx4 v[216:217], off
	v_lshl_add_u64 v[216:217], v[222:223], 0, s[8:9]
	s_mov_b32 m0, s51
	s_nop 0
	global_load_lds_dwordx4 v[216:217], off
	s_waitcnt vmcnt(8)
	s_waitcnt lgkmcnt(0)
	s_barrier
	s_setprio 1
	v_mfma_f32_16x16x32_bf16 v[62:65], v[146:149], v[184:187], v[62:65]
	v_mfma_f32_16x16x32_bf16 v[54:57], v[160:163], v[184:187], v[54:57]
	v_mfma_f32_16x16x32_bf16 v[46:49], v[146:149], v[192:195], v[46:49]
	v_mfma_f32_16x16x32_bf16 v[38:41], v[160:163], v[192:195], v[38:41]
	v_mfma_f32_16x16x32_bf16 v[30:33], v[146:149], v[200:203], v[30:33]
	v_mfma_f32_16x16x32_bf16 v[22:25], v[160:163], v[200:203], v[22:25]
	v_mfma_f32_16x16x32_bf16 v[14:17], v[146:149], v[208:211], v[14:17]
	v_mfma_f32_16x16x32_bf16 v[6:9], v[160:163], v[208:211], v[6:9]
	v_mfma_f32_16x16x32_bf16 v[62:65], v[156:159], v[188:191], v[62:65]
	v_mfma_f32_16x16x32_bf16 v[54:57], v[164:167], v[188:191], v[54:57]
	v_mfma_f32_16x16x32_bf16 v[46:49], v[156:159], v[196:199], v[46:49]
	v_mfma_f32_16x16x32_bf16 v[38:41], v[164:167], v[196:199], v[38:41]
	v_mfma_f32_16x16x32_bf16 v[30:33], v[156:159], v[204:207], v[30:33]
	v_mfma_f32_16x16x32_bf16 v[22:25], v[164:167], v[204:207], v[22:25]
	v_mfma_f32_16x16x32_bf16 v[14:17], v[156:159], v[212:215], v[14:17]
	v_mfma_f32_16x16x32_bf16 v[6:9], v[164:167], v[212:215], v[6:9]
	s_setprio 0
	s_setprio 1
	v_mfma_f32_16x16x32_bf16 v[58:61], v[168:171], v[184:187], v[58:61]
	v_mfma_f32_16x16x32_bf16 v[50:53], v[176:179], v[184:187], v[50:53]
	v_mfma_f32_16x16x32_bf16 v[42:45], v[168:171], v[192:195], v[42:45]
	v_mfma_f32_16x16x32_bf16 v[34:37], v[176:179], v[192:195], v[34:37]
	v_mfma_f32_16x16x32_bf16 v[26:29], v[168:171], v[200:203], v[26:29]
	v_mfma_f32_16x16x32_bf16 v[18:21], v[176:179], v[200:203], v[18:21]
	v_mfma_f32_16x16x32_bf16 v[10:13], v[168:171], v[208:211], v[10:13]
	v_mfma_f32_16x16x32_bf16 v[2:5], v[176:179], v[208:211], v[2:5]
	v_mfma_f32_16x16x32_bf16 v[58:61], v[172:175], v[188:191], v[58:61]
	v_mfma_f32_16x16x32_bf16 v[50:53], v[180:183], v[188:191], v[50:53]
	v_mfma_f32_16x16x32_bf16 v[42:45], v[172:175], v[196:199], v[42:45]
	v_mfma_f32_16x16x32_bf16 v[34:37], v[180:183], v[196:199], v[34:37]
	v_mfma_f32_16x16x32_bf16 v[26:29], v[172:175], v[204:207], v[26:29]
	v_mfma_f32_16x16x32_bf16 v[18:21], v[180:183], v[204:207], v[18:21]
	v_mfma_f32_16x16x32_bf16 v[10:13], v[172:175], v[212:215], v[10:13]
	v_mfma_f32_16x16x32_bf16 v[2:5], v[180:183], v[212:215], v[2:5]
	s_setprio 0
	s_barrier
	s_add_i32 s61, s61, 2
	s_add_u32 s34, s34, 0x100
	s_addc_u32 s35, s35, 0
	s_add_u32 s59, s59, 0x100
	s_addc_u32 s60, s60, 0
	s_cmp_gt_u32 s61, 13
	s_cbranch_scc0 .LBB0_74
	s_and_b64 vcc, exec, s[10:11]
	s_cbranch_vccz .LBB0_77
	s_barrier

; #define PG8_STAGE(bufoff, gbase, voff) do { _Pragma("unroll") for (int _i = 0; _i < 2; ++_i) \
;         __builtin_amdgcn_global_load_lds((const unsigned*)((const char*)(gbase) + (voff)[_i]), (LAS unsigned*)(lds + (bufoff) + ldsw + _i * 8192), 16, 0, 0); } while (0)
; #define PG8_LDA(dst, b, h) do { _Pragma("unroll") for (int m = 0; m < 4; ++m) _Pragma("unroll") for (int k = 0; k < 2; ++k) dst[m][k] = *(const LAS bf16x8*)(lds + PG8_SA(b, h) + aoff + m * 2048 + k * 1024); } while (0)
; #define PG8_LDB(dst, b, h) do { _Pragma("unroll") for (int n = 0; n < 2; ++n) _Pragma("unroll") for (int k = 0; k < 2; ++k) dst[n][k] = *(const LAS bf16x8*)(lds + PG8_SB(b, h) + boff + n * 2048 + k * 1024); } while (0)
; #define PG8_MMA(ai, bj, At, Bt) do { __builtin_amdgcn_s_setprio(1); _Pragma("unroll") for (int m = 0; m < 4; ++m) _Pragma("unroll") for (int n = 0; n < 2; ++n) _Pragma("unroll") for (int k = 0; k < 2; ++k) \
;         acc[ai][bj][m][n] = __builtin_amdgcn_mfma_f32_16x16x32_bf16(Bt[n][k], At[m][k], acc[ai][bj][m][n], 0, 0, 0); __builtin_amdgcn_s_setprio(0); } while (0)
; #define PG8_WAIT_V(n) asm volatile("s_waitcnt vmcnt(" #n ")" ::: "memory")
; #define PG8_WAIT_L(n) asm volatile("s_waitcnt lgkmcnt(" #n ")" ::: "memory")
; #define PG8_BAR __builtin_amdgcn_s_barrier()
; #define PG8_SCHED __builtin_amdgcn_sched_barrier(0)
; template <class Epi>
; __device__ __forceinline__ void gemm_phase(LAS unsigned char* lds, const Gemm g, const StaticOrder& S, const Epi& E) {
;     ...
;             PG8_LDB(B0, 0, 0); PG8_LDB(B1, 0, 1); PG8_SCHED; PG8_LDA(At, 0, 0); PG8_STAGE(PG8_SA(1, 1), a1 + hstep, voffA);
;             PG8_WAIT_V(8); PG8_WAIT_L(0); PG8_BAR; PG8_MMA(0, 0, At, B0); PG8_MMA(0, 1, At, B1); PG8_BAR; PG8_SCHED;
;             PG8_LDA(At, 0, 1); PG8_STAGE(PG8_SB(0, 0), b2, voffB); PG8_STAGE(PG8_SB(0, 1), b2 + hstep, voffB); PG8_STAGE(PG8_SA(0, 0), a2, voffA);
;             PG8_WAIT_V(8); PG8_WAIT_L(0); PG8_BAR; PG8_MMA(1, 0, At, B0); PG8_MMA(1, 1, At, B1); PG8_BAR; PG8_SCHED;
.LBB0_164:
	ds_read_b128 v[150:153], v147
	ds_read_b128 v[154:157], v147 offset:1024
	ds_read_b128 v[158:161], v147 offset:2048
	ds_read_b128 v[162:165], v147 offset:3072
	ds_read_b128 v[166:169], v148
	ds_read_b128 v[170:173], v148 offset:1024
	ds_read_b128 v[174:177], v148 offset:2048
	ds_read_b128 v[178:181], v148 offset:3072
	s_add_u32 s34, s30, 0xfff50080
	s_addc_u32 s35, s31, -1
	s_cmp_eq_u32 s74, 40
	s_cselect_b32 s53, s5, s35
	s_cselect_b32 s52, s4, s34
	s_cselect_b32 s35, s29, s73
	s_cselect_b32 s34, s28, s72
	v_lshl_add_u64 v[142:143], s[30:31], 0, v[134:135]
	s_add_i32 m0, s58, 0xc000
	ds_read_b128 v[182:185], v149
	ds_read_b128 v[186:189], v149 offset:1024
	ds_read_b128 v[190:193], v149 offset:2048
	ds_read_b128 v[194:197], v149 offset:3072
	ds_read_b128 v[198:201], v149 offset:4096
	ds_read_b128 v[202:205], v149 offset:5120
	ds_read_b128 v[206:209], v149 offset:6144
	ds_read_b128 v[210:213], v149 offset:7168
	global_load_lds_dwordx4 v[142:143], off
	v_lshl_add_u64 v[142:143], s[30:31], 0, v[136:137]
	s_add_i32 m0, s58, 0xe000
	s_nop 0
	global_load_lds_dwordx4 v[142:143], off
	s_waitcnt vmcnt(8)
	s_waitcnt lgkmcnt(0)
	s_barrier
	s_setprio 1
	v_mfma_f32_16x16x32_bf16 v[126:129], v[150:153], v[182:185], v[126:129]
	v_mfma_f32_16x16x32_bf16 v[122:125], v[158:161], v[182:185], v[122:125]
	v_mfma_f32_16x16x32_bf16 v[114:117], v[150:153], v[190:193], v[114:117]
	v_mfma_f32_16x16x32_bf16 v[106:109], v[158:161], v[190:193], v[106:109]
	v_mfma_f32_16x16x32_bf16 v[98:101], v[150:153], v[198:201], v[98:101]
	v_mfma_f32_16x16x32_bf16 v[90:93], v[158:161], v[198:201], v[90:93]
	v_mfma_f32_16x16x32_bf16 v[82:85], v[150:153], v[206:209], v[82:85]
	v_mfma_f32_16x16x32_bf16 v[74:77], v[158:161], v[206:209], v[74:77]
	v_mfma_f32_16x16x32_bf16 v[126:129], v[154:157], v[186:189], v[126:129]
	v_mfma_f32_16x16x32_bf16 v[122:125], v[162:165], v[186:189], v[122:125]
	v_mfma_f32_16x16x32_bf16 v[114:117], v[154:157], v[194:197], v[114:117]
	v_mfma_f32_16x16x32_bf16 v[106:109], v[162:165], v[194:197], v[106:109]
	v_mfma_f32_16x16x32_bf16 v[98:101], v[154:157], v[202:205], v[98:101]
	v_mfma_f32_16x16x32_bf16 v[90:93], v[162:165], v[202:205], v[90:93]
	v_mfma_f32_16x16x32_bf16 v[82:85], v[154:157], v[210:213], v[82:85]
	v_mfma_f32_16x16x32_bf16 v[74:77], v[162:165], v[210:213], v[74:77]
	s_setprio 0
	s_setprio 1
	v_mfma_f32_16x16x32_bf16 v[118:121], v[166:169], v[182:185], v[118:121]
	v_mfma_f32_16x16x32_bf16 v[110:113], v[174:177], v[182:185], v[110:113]
	v_mfma_f32_16x16x32_bf16 v[102:105], v[166:169], v[190:193], v[102:105]
	v_mfma_f32_16x16x32_bf16 v[94:97], v[174:177], v[190:193], v[94:97]
	v_mfma_f32_16x16x32_bf16 v[86:89], v[166:169], v[198:201], v[86:89]
	v_mfma_f32_16x16x32_bf16 v[78:81], v[174:177], v[198:201], v[78:81]
	v_mfma_f32_16x16x32_bf16 v[70:73], v[166:169], v[206:209], v[70:73]
	v_mfma_f32_16x16x32_bf16 v[66:69], v[174:177], v[206:209], v[66:69]
	v_mfma_f32_16x16x32_bf16 v[118:121], v[170:173], v[186:189], v[118:121]
	v_mfma_f32_16x16x32_bf16 v[110:113], v[178:181], v[186:189], v[110:113]
	v_mfma_f32_16x16x32_bf16 v[102:105], v[170:173], v[194:197], v[102:105]
	v_mfma_f32_16x16x32_bf16 v[94:97], v[178:181], v[194:197], v[94:97]
	v_mfma_f32_16x16x32_bf16 v[86:89], v[170:173], v[202:205], v[86:89]
	v_mfma_f32_16x16x32_bf16 v[78:81], v[178:181], v[202:205], v[78:81]
	v_mfma_f32_16x16x32_bf16 v[70:73], v[170:173], v[210:213], v[70:73]
	v_mfma_f32_16x16x32_bf16 v[66:69], v[178:181], v[210:213], v[66:69]
	s_setprio 0
	s_barrier
	s_add_i32 s75, s66, s57
	v_lshl_add_u64 v[142:143], s[34:35], 0, v[130:131]
	s_mov_b32 m0, s75
	ds_read_b128 v[182:185], v149 offset:16384
	ds_read_b128 v[186:189], v149 offset:17408
	ds_read_b128 v[190:193], v149 offset:18432
	ds_read_b128 v[194:197], v149 offset:19456
	ds_read_b128 v[198:201], v149 offset:20480
	ds_read_b128 v[202:205], v149 offset:21504
	ds_read_b128 v[206:209], v149 offset:22528
	ds_read_b128 v[210:213], v149 offset:23552
	global_load_lds_dwordx4 v[142:143], off
	s_add_i32 m0, s75, 0x2000
	s_add_u32 s76, s34, 0xb0000
	v_lshl_add_u64 v[214:215], s[34:35], 0, v[132:133]
	s_addc_u32 s77, s35, 0
	s_add_i32 s75, s67, s57
	global_load_lds_dwordx4 v[214:215], off
	v_lshl_add_u64 v[216:217], s[76:77], 0, v[130:131]
	s_mov_b32 m0, s75
	v_lshl_add_u64 v[218:219], s[52:53], 0, v[132:133]
	global_load_lds_dwordx4 v[216:217], off
	v_lshl_add_u64 v[216:217], s[76:77], 0, v[132:133]
	s_add_i32 m0, s75, 0x2000
	s_nop 0
	global_load_lds_dwordx4 v[216:217], off
	v_lshl_add_u64 v[216:217], s[52:53], 0, v[130:131]
	s_mov_b32 m0, s58
	s_nop 0
	global_load_lds_dwordx4 v[216:217], off
	s_mov_b32 m0, s59
	s_nop 0
	global_load_lds_dwordx4 v[218:219], off
	s_waitcnt vmcnt(8)
	s_waitcnt lgkmcnt(0)
	s_barrier
; #define PG8_STAGE(bufoff, gbase, voff) do { _Pragma("unroll") for (int _i = 0; _i < 2; ++_i) \
;         __builtin_amdgcn_global_load_lds((const unsigned*)((const char*)(gbase) + (voff)[_i]), (LAS unsigned*)(lds + (bufoff) + ldsw + _i * 8192), 16, 0, 0); } while (0)
; #define PG8_LDA(dst, b, h) do { _Pragma("unroll") for (int m = 0; m < 4; ++m) _Pragma("unroll") for (int k = 0; k < 2; ++k) dst[m][k] = *(const LAS bf16x8*)(lds + PG8_SA(b, h) + aoff + m * 2048 + k * 1024); } while (0)
; #define PG8_LDB(dst, b, h) do { _Pragma("unroll") for (int n = 0; n < 2; ++n) _Pragma("unroll") for (int k = 0; k < 2; ++k) dst[n][k] = *(const LAS bf16x8*)(lds + PG8_SB(b, h) + boff + n * 2048 + k * 1024); } while (0)
; #define PG8_MMA(ai, bj, At, Bt) do { __builtin_amdgcn_s_setprio(1); _Pragma("unroll") for (int m = 0; m < 4; ++m) _Pragma("unroll") for (int n = 0; n < 2; ++n) _Pragma("unroll") for (int k = 0; k < 2; ++k) \
;         acc[ai][bj][m][n] = __builtin_amdgcn_mfma_f32_16x16x32_bf16(Bt[n][k], At[m][k], acc[ai][bj][m][n], 0, 0, 0); __builtin_amdgcn_s_setprio(0); } while (0)
; #define PG8_WAIT_V(n) asm volatile("s_waitcnt vmcnt(" #n ")" ::: "memory")
; #define PG8_WAIT_L(n) asm volatile("s_waitcnt lgkmcnt(" #n ")" ::: "memory")
; #define PG8_BAR __builtin_amdgcn_s_barrier()
; #define PG8_SCHED __builtin_amdgcn_sched_barrier(0)
; template <class Epi>
; __device__ __forceinline__ void gemm_phase(LAS unsigned char* lds, const Gemm g, const StaticOrder& S, const Epi& E) {
;     ...
;             PG8_WAIT_V(8); PG8_WAIT_L(0); PG8_BAR; PG8_MMA(1, 0, At, B0); PG8_MMA(1, 1, At, B1); PG8_BAR; PG8_SCHED;
;             PG8_LDB(B0, 1, 0); PG8_LDB(B1, 1, 1); PG8_SCHED; PG8_LDA(At, 1, 0); PG8_STAGE(PG8_SA(0, 1), a2 + hstep, voffA);
;             PG8_WAIT_V(8); PG8_WAIT_L(0); PG8_BAR; PG8_MMA(0, 0, At, B0); PG8_MMA(0, 1, At, B1); PG8_BAR; PG8_SCHED;
;             PG8_LDA(At, 1, 1); PG8_STAGE(PG8_SB(1, 0), b3, voffB); PG8_STAGE(PG8_SB(1, 1), b3 + hstep, voffB); PG8_STAGE(PG8_SA(1, 0), a3, voffA);
	s_setprio 1
	v_mfma_f32_16x16x32_bf16 v[62:65], v[150:153], v[182:185], v[62:65]
	v_mfma_f32_16x16x32_bf16 v[58:61], v[158:161], v[182:185], v[58:61]
	v_mfma_f32_16x16x32_bf16 v[50:53], v[150:153], v[190:193], v[50:53]
	v_mfma_f32_16x16x32_bf16 v[42:45], v[158:161], v[190:193], v[42:45]
	v_mfma_f32_16x16x32_bf16 v[34:37], v[150:153], v[198:201], v[34:37]
	v_mfma_f32_16x16x32_bf16 v[26:29], v[158:161], v[198:201], v[26:29]
	v_mfma_f32_16x16x32_bf16 v[18:21], v[150:153], v[206:209], v[18:21]
	v_mfma_f32_16x16x32_bf16 v[10:13], v[158:161], v[206:209], v[10:13]
	v_mfma_f32_16x16x32_bf16 v[62:65], v[154:157], v[186:189], v[62:65]
	v_mfma_f32_16x16x32_bf16 v[58:61], v[162:165], v[186:189], v[58:61]
	v_mfma_f32_16x16x32_bf16 v[50:53], v[154:157], v[194:197], v[50:53]
	v_mfma_f32_16x16x32_bf16 v[42:45], v[162:165], v[194:197], v[42:45]
	v_mfma_f32_16x16x32_bf16 v[34:37], v[154:157], v[202:205], v[34:37]
	v_mfma_f32_16x16x32_bf16 v[26:29], v[162:165], v[202:205], v[26:29]
	v_mfma_f32_16x16x32_bf16 v[18:21], v[154:157], v[210:213], v[18:21]
	v_mfma_f32_16x16x32_bf16 v[10:13], v[162:165], v[210:213], v[10:13]
	s_setprio 0
	s_setprio 1
	v_mfma_f32_16x16x32_bf16 v[54:57], v[166:169], v[182:185], v[54:57]
	v_mfma_f32_16x16x32_bf16 v[46:49], v[174:177], v[182:185], v[46:49]
	v_mfma_f32_16x16x32_bf16 v[38:41], v[166:169], v[190:193], v[38:41]
	v_mfma_f32_16x16x32_bf16 v[30:33], v[174:177], v[190:193], v[30:33]
	v_mfma_f32_16x16x32_bf16 v[22:25], v[166:169], v[198:201], v[22:25]
	v_mfma_f32_16x16x32_bf16 v[14:17], v[174:177], v[198:201], v[14:17]
	v_mfma_f32_16x16x32_bf16 v[6:9], v[166:169], v[206:209], v[6:9]
	v_mfma_f32_16x16x32_bf16 v[2:5], v[174:177], v[206:209], v[2:5]
	v_mfma_f32_16x16x32_bf16 v[54:57], v[170:173], v[186:189], v[54:57]
	v_mfma_f32_16x16x32_bf16 v[46:49], v[178:181], v[186:189], v[46:49]
	v_mfma_f32_16x16x32_bf16 v[38:41], v[170:173], v[194:197], v[38:41]
	v_mfma_f32_16x16x32_bf16 v[30:33], v[178:181], v[194:197], v[30:33]
	v_mfma_f32_16x16x32_bf16 v[22:25], v[170:173], v[202:205], v[22:25]
	v_mfma_f32_16x16x32_bf16 v[14:17], v[178:181], v[202:205], v[14:17]
	v_mfma_f32_16x16x32_bf16 v[6:9], v[170:173], v[210:213], v[6:9]
	v_mfma_f32_16x16x32_bf16 v[2:5], v[178:181], v[210:213], v[2:5]
	s_setprio 0
	s_barrier
	s_add_i32 s75, 0, 0x18000
	s_add_i32 s76, 0, 0x1c000
	v_add_u32_e32 v162, s75, v145
	v_add_u32_e32 v178, s76, v145
	ds_read_b128 v[150:153], v162
	ds_read_b128 v[154:157], v162 offset:1024
	ds_read_b128 v[158:161], v162 offset:2048
	ds_read_b128 v[162:165], v162 offset:3072
	ds_read_b128 v[166:169], v178
	ds_read_b128 v[170:173], v178 offset:1024
	ds_read_b128 v[174:177], v178 offset:2048
	ds_read_b128 v[178:181], v178 offset:3072
	s_add_u32 s52, s52, 0xb0000
	s_addc_u32 s53, s53, 0
	s_mov_b32 m0, s60
	v_lshl_add_u64 v[220:221], s[52:53], 0, v[130:131]
	ds_read_b128 v[182:185], v149 offset:32768
	ds_read_b128 v[186:189], v149 offset:33792
	ds_read_b128 v[190:193], v149 offset:34816
	ds_read_b128 v[194:197], v149 offset:35840
	ds_read_b128 v[198:201], v149 offset:36864
	ds_read_b128 v[202:205], v149 offset:37888
	ds_read_b128 v[206:209], v149 offset:38912
	ds_read_b128 v[210:213], v149 offset:39936
	global_load_lds_dwordx4 v[220:221], off
	v_lshl_add_u64 v[220:221], s[52:53], 0, v[132:133]
	s_mov_b32 m0, s61
	s_nop 0
	global_load_lds_dwordx4 v[220:221], off
	s_waitcnt vmcnt(8)
	s_waitcnt lgkmcnt(0)
	s_barrier
	s_setprio 1
	v_mfma_f32_16x16x32_bf16 v[126:129], v[150:153], v[182:185], v[126:129]
	v_mfma_f32_16x16x32_bf16 v[122:125], v[158:161], v[182:185], v[122:125]
	v_mfma_f32_16x16x32_bf16 v[114:117], v[150:153], v[190:193], v[114:117]
	v_mfma_f32_16x16x32_bf16 v[106:109], v[158:161], v[190:193], v[106:109]
	v_mfma_f32_16x16x32_bf16 v[98:101], v[150:153], v[198:201], v[98:101]
	v_mfma_f32_16x16x32_bf16 v[90:93], v[158:161], v[198:201], v[90:93]
	v_mfma_f32_16x16x32_bf16 v[82:85], v[150:153], v[206:209], v[82:85]
	v_mfma_f32_16x16x32_bf16 v[74:77], v[158:161], v[206:209], v[74:77]
	v_mfma_f32_16x16x32_bf16 v[126:129], v[154:157], v[186:189], v[126:129]
	v_mfma_f32_16x16x32_bf16 v[122:125], v[162:165], v[186:189], v[122:125]
	v_mfma_f32_16x16x32_bf16 v[114:117], v[154:157], v[194:197], v[114:117]
	v_mfma_f32_16x16x32_bf16 v[106:109], v[162:165], v[194:197], v[106:109]
	v_mfma_f32_16x16x32_bf16 v[98:101], v[154:157], v[202:205], v[98:101]
	v_mfma_f32_16x16x32_bf16 v[90:93], v[162:165], v[202:205], v[90:93]
	v_mfma_f32_16x16x32_bf16 v[82:85], v[154:157], v[210:213], v[82:85]
	v_mfma_f32_16x16x32_bf16 v[74:77], v[162:165], v[210:213], v[74:77]
	s_setprio 0
	s_setprio 1
	v_mfma_f32_16x16x32_bf16 v[118:121], v[166:169], v[182:185], v[118:121]
	v_mfma_f32_16x16x32_bf16 v[110:113], v[174:177], v[182:185], v[110:113]
	v_mfma_f32_16x16x32_bf16 v[102:105], v[166:169], v[190:193], v[102:105]
	v_mfma_f32_16x16x32_bf16 v[94:97], v[174:177], v[190:193], v[94:97]
	v_mfma_f32_16x16x32_bf16 v[86:89], v[166:169], v[198:201], v[86:89]
	v_mfma_f32_16x16x32_bf16 v[78:81], v[174:177], v[198:201], v[78:81]
	v_mfma_f32_16x16x32_bf16 v[70:73], v[166:169], v[206:209], v[70:73]
	v_mfma_f32_16x16x32_bf16 v[66:69], v[174:177], v[206:209], v[66:69]
	v_mfma_f32_16x16x32_bf16 v[118:121], v[170:173], v[186:189], v[118:121]
	v_mfma_f32_16x16x32_bf16 v[110:113], v[178:181], v[186:189], v[110:113]
	v_mfma_f32_16x16x32_bf16 v[102:105], v[170:173], v[194:197], v[102:105]
	v_mfma_f32_16x16x32_bf16 v[94:97], v[178:181], v[194:197], v[94:97]
	v_mfma_f32_16x16x32_bf16 v[86:89], v[170:173], v[202:205], v[86:89]
	v_mfma_f32_16x16x32_bf16 v[78:81], v[178:181], v[202:205], v[78:81]
	v_mfma_f32_16x16x32_bf16 v[70:73], v[170:173], v[210:213], v[70:73]
	v_mfma_f32_16x16x32_bf16 v[66:69], v[178:181], v[210:213], v[66:69]
	s_setprio 0
	s_barrier
; #define PG8_STAGE(bufoff, gbase, voff) do { _Pragma("unroll") for (int _i = 0; _i < 2; ++_i) \
;         __builtin_amdgcn_global_load_lds((const unsigned*)((const char*)(gbase) + (voff)[_i]), (LAS unsigned*)(lds + (bufoff) + ldsw + _i * 8192), 16, 0, 0); } while (0)
; #define PG8_LDA(dst, b, h) do { _Pragma("unroll") for (int m = 0; m < 4; ++m) _Pragma("unroll") for (int k = 0; k < 2; ++k) dst[m][k] = *(const LAS bf16x8*)(lds + PG8_SA(b, h) + aoff + m * 2048 + k * 1024); } while (0)
; #define PG8_MMA(ai, bj, At, Bt) do { __builtin_amdgcn_s_setprio(1); _Pragma("unroll") for (int m = 0; m < 4; ++m) _Pragma("unroll") for (int n = 0; n < 2; ++n) _Pragma("unroll") for (int k = 0; k < 2; ++k) \
;         acc[ai][bj][m][n] = __builtin_amdgcn_mfma_f32_16x16x32_bf16(Bt[n][k], At[m][k], acc[ai][bj][m][n], 0, 0, 0); __builtin_amdgcn_s_setprio(0); } while (0)
; #define PG8_WAIT_V(n) asm volatile("s_waitcnt vmcnt(" #n ")" ::: "memory")
; #define PG8_WAIT_L(n) asm volatile("s_waitcnt lgkmcnt(" #n ")" ::: "memory")
; #define PG8_BAR __builtin_amdgcn_s_barrier()
; #define PG8_SCHED __builtin_amdgcn_sched_barrier(0)
; template <class Epi>
; __device__ __forceinline__ void gemm_phase(LAS unsigned char* lds, const Gemm g, const StaticOrder& S, const Epi& E) {
;     ...
;             PG8_LDA(At, 1, 1); PG8_STAGE(PG8_SB(1, 0), b3, voffB); PG8_STAGE(PG8_SB(1, 1), b3 + hstep, voffB); PG8_STAGE(PG8_SA(1, 0), a3, voffA);
;             PG8_WAIT_V(8); PG8_WAIT_L(0); PG8_BAR; PG8_MMA(1, 0, At, B0); PG8_MMA(1, 1, At, B1); PG8_BAR; PG8_SCHED;
;         }
	s_add_i32 s52, s75, s57
	v_lshl_add_u64 v[142:143], v[142:143], 0, s[6:7]
	s_mov_b32 m0, s52
	ds_read_b128 v[182:185], v149 offset:49152
	ds_read_b128 v[186:189], v149 offset:50176
	ds_read_b128 v[190:193], v149 offset:51200
	ds_read_b128 v[194:197], v149 offset:52224
	ds_read_b128 v[198:201], v149 offset:53248
	ds_read_b128 v[202:205], v149 offset:54272
	ds_read_b128 v[206:209], v149 offset:55296
	ds_read_b128 v[210:213], v149 offset:56320
	global_load_lds_dwordx4 v[142:143], off
	s_add_i32 m0, s52, 0x2000
	s_add_u32 s34, s34, 0xb0080
	v_lshl_add_u64 v[142:143], v[214:215], 0, s[6:7]
	s_addc_u32 s35, s35, 0
	s_add_i32 s52, s76, s57
	global_load_lds_dwordx4 v[142:143], off
	v_lshl_add_u64 v[142:143], s[34:35], 0, v[130:131]
	s_mov_b32 m0, s52
	s_nop 0
	global_load_lds_dwordx4 v[142:143], off
	v_lshl_add_u64 v[142:143], s[34:35], 0, v[132:133]
	s_add_i32 m0, s52, 0x2000
	s_nop 0
	global_load_lds_dwordx4 v[142:143], off
	v_lshl_add_u64 v[142:143], v[216:217], 0, s[6:7]
	s_mov_b32 m0, s63
	s_nop 0
	global_load_lds_dwordx4 v[142:143], off
	v_lshl_add_u64 v[142:143], v[218:219], 0, s[6:7]
	s_mov_b32 m0, s64
	s_nop 0
	global_load_lds_dwordx4 v[142:143], off
	s_waitcnt vmcnt(8)
	s_waitcnt lgkmcnt(0)
	s_barrier
	s_setprio 1
	v_mfma_f32_16x16x32_bf16 v[62:65], v[150:153], v[182:185], v[62:65]
	v_mfma_f32_16x16x32_bf16 v[58:61], v[158:161], v[182:185], v[58:61]
	v_mfma_f32_16x16x32_bf16 v[50:53], v[150:153], v[190:193], v[50:53]
	v_mfma_f32_16x16x32_bf16 v[42:45], v[158:161], v[190:193], v[42:45]
	v_mfma_f32_16x16x32_bf16 v[34:37], v[150:153], v[198:201], v[34:37]
	v_mfma_f32_16x16x32_bf16 v[26:29], v[158:161], v[198:201], v[26:29]
	v_mfma_f32_16x16x32_bf16 v[18:21], v[150:153], v[206:209], v[18:21]
	v_mfma_f32_16x16x32_bf16 v[10:13], v[158:161], v[206:209], v[10:13]
	v_mfma_f32_16x16x32_bf16 v[62:65], v[154:157], v[186:189], v[62:65]
	v_mfma_f32_16x16x32_bf16 v[58:61], v[162:165], v[186:189], v[58:61]
	v_mfma_f32_16x16x32_bf16 v[50:53], v[154:157], v[194:197], v[50:53]
	v_mfma_f32_16x16x32_bf16 v[42:45], v[162:165], v[194:197], v[42:45]
	v_mfma_f32_16x16x32_bf16 v[34:37], v[154:157], v[202:205], v[34:37]
	v_mfma_f32_16x16x32_bf16 v[26:29], v[162:165], v[202:205], v[26:29]
	v_mfma_f32_16x16x32_bf16 v[18:21], v[154:157], v[210:213], v[18:21]
	v_mfma_f32_16x16x32_bf16 v[10:13], v[162:165], v[210:213], v[10:13]
	s_setprio 0
	s_setprio 1
	v_mfma_f32_16x16x32_bf16 v[54:57], v[166:169], v[182:185], v[54:57]
	v_mfma_f32_16x16x32_bf16 v[46:49], v[174:177], v[182:185], v[46:49]
	v_mfma_f32_16x16x32_bf16 v[38:41], v[166:169], v[190:193], v[38:41]
	v_mfma_f32_16x16x32_bf16 v[30:33], v[174:177], v[190:193], v[30:33]
	v_mfma_f32_16x16x32_bf16 v[22:25], v[166:169], v[198:201], v[22:25]
	v_mfma_f32_16x16x32_bf16 v[14:17], v[174:177], v[198:201], v[14:17]
	v_mfma_f32_16x16x32_bf16 v[6:9], v[166:169], v[206:209], v[6:9]
	v_mfma_f32_16x16x32_bf16 v[2:5], v[174:177], v[206:209], v[2:5]
	v_mfma_f32_16x16x32_bf16 v[54:57], v[170:173], v[186:189], v[54:57]
	v_mfma_f32_16x16x32_bf16 v[46:49], v[178:181], v[186:189], v[46:49]
	v_mfma_f32_16x16x32_bf16 v[38:41], v[170:173], v[194:197], v[38:41]
	v_mfma_f32_16x16x32_bf16 v[30:33], v[178:181], v[194:197], v[30:33]
	v_mfma_f32_16x16x32_bf16 v[22:25], v[170:173], v[202:205], v[22:25]
	v_mfma_f32_16x16x32_bf16 v[14:17], v[178:181], v[202:205], v[14:17]
	v_mfma_f32_16x16x32_bf16 v[6:9], v[170:173], v[210:213], v[6:9]
	v_mfma_f32_16x16x32_bf16 v[2:5], v[178:181], v[210:213], v[2:5]
	s_setprio 0
	s_barrier
	s_add_i32 s74, s74, 2
	s_add_u32 s30, s30, 0x100
	s_addc_u32 s31, s31, 0
	s_add_u32 s72, s72, 0x100
	s_addc_u32 s73, s73, 0
	s_cmp_gt_u32 s74, 41
	s_cbranch_scc0 .LBB0_164
	s_and_b64 vcc, exec, s[8:9]
	s_cbranch_vccz .LBB0_167
	s_barrier

; #define PG8_STAGE(bufoff, gbase, voff) do { _Pragma("unroll") for (int _i = 0; _i < 2; ++_i) \
;         __builtin_amdgcn_global_load_lds((const unsigned*)((const char*)(gbase) + (voff)[_i]), (LAS unsigned*)(lds + (bufoff) + ldsw + _i * 8192), 16, 0, 0); } while (0)
; #define PG8_LDA(dst, b, h) do { _Pragma("unroll") for (int m = 0; m < 4; ++m) _Pragma("unroll") for (int k = 0; k < 2; ++k) dst[m][k] = *(const LAS bf16x8*)(lds + PG8_SA(b, h) + aoff + m * 2048 + k * 1024); } while (0)
; #define PG8_LDB(dst, b, h) do { _Pragma("unroll") for (int n = 0; n < 2; ++n) _Pragma("unroll") for (int k = 0; k < 2; ++k) dst[n][k] = *(const LAS bf16x8*)(lds + PG8_SB(b, h) + boff + n * 2048 + k * 1024); } while (0)
; #define PG8_MMA(ai, bj, At, Bt) do { __builtin_amdgcn_s_setprio(1); _Pragma("unroll") for (int m = 0; m < 4; ++m) _Pragma("unroll") for (int n = 0; n < 2; ++n) _Pragma("unroll") for (int k = 0; k < 2; ++k) \
;         acc[ai][bj][m][n] = __builtin_amdgcn_mfma_f32_16x16x32_bf16(Bt[n][k], At[m][k], acc[ai][bj][m][n], 0, 0, 0); __builtin_amdgcn_s_setprio(0); } while (0)
; #define PG8_WAIT_V(n) asm volatile("s_waitcnt vmcnt(" #n ")" ::: "memory")
; #define PG8_WAIT_L(n) asm volatile("s_waitcnt lgkmcnt(" #n ")" ::: "memory")
; #define PG8_BAR __builtin_amdgcn_s_barrier()
; #define PG8_SCHED __builtin_amdgcn_sched_barrier(0)
; template <class Epi>
; __device__ __forceinline__ void gemm_phase(LAS unsigned char* lds, const Gemm g, const StaticOrder& S, const Epi& E) {
;     ...
;             PG8_LDB(B0, 0, 0); PG8_LDB(B1, 0, 1); PG8_SCHED; PG8_LDA(At, 0, 0); PG8_STAGE(PG8_SA(1, 1), a1 + hstep, voffA);
;             PG8_WAIT_V(8); PG8_WAIT_L(0); PG8_BAR; PG8_MMA(0, 0, At, B0); PG8_MMA(0, 1, At, B1); PG8_BAR; PG8_SCHED;
;             PG8_LDA(At, 0, 1); PG8_STAGE(PG8_SB(0, 0), b2, voffB); PG8_STAGE(PG8_SB(0, 1), b2 + hstep, voffB); PG8_STAGE(PG8_SA(0, 0), a2, voffA);
;             PG8_WAIT_V(8); PG8_WAIT_L(0); PG8_BAR; PG8_MMA(1, 0, At, B0); PG8_MMA(1, 1, At, B1); PG8_BAR; PG8_SCHED;
.LBB0_314:
	ds_read_b128 v[152:155], v149
	ds_read_b128 v[156:159], v149 offset:1024
	ds_read_b128 v[160:163], v149 offset:2048
	ds_read_b128 v[164:167], v149 offset:3072
	ds_read_b128 v[168:171], v150
	ds_read_b128 v[172:175], v150 offset:1024
	ds_read_b128 v[176:179], v150 offset:2048
	ds_read_b128 v[180:183], v150 offset:3072
	s_add_u32 s22, s20, 0xfffc0080
	s_addc_u32 s23, s21, -1
	s_cmp_eq_u32 s65, 12
	s_cselect_b32 s29, s15, s23
	s_cselect_b32 s28, s61, s22
	s_cselect_b32 s23, s13, s64
	s_cselect_b32 s22, s62, s63
	v_lshl_add_u64 v[216:217], s[20:21], 0, v[138:139]
	s_add_i32 m0, s11, 0xc000
	ds_read_b128 v[184:187], v151
	ds_read_b128 v[188:191], v151 offset:1024
	ds_read_b128 v[192:195], v151 offset:2048
	ds_read_b128 v[196:199], v151 offset:3072
	ds_read_b128 v[200:203], v151 offset:4096
	ds_read_b128 v[204:207], v151 offset:5120
	ds_read_b128 v[208:211], v151 offset:6144
	ds_read_b128 v[212:215], v151 offset:7168
	global_load_lds_dwordx4 v[216:217], off
	v_lshl_add_u64 v[216:217], s[20:21], 0, v[140:141]
	s_add_i32 m0, s11, 0xe000
	s_nop 0
	global_load_lds_dwordx4 v[216:217], off
	s_waitcnt vmcnt(8)
	s_waitcnt lgkmcnt(0)
	s_barrier
	s_setprio 1
	v_mfma_f32_16x16x32_bf16 v[126:129], v[152:155], v[184:187], v[126:129]
	v_mfma_f32_16x16x32_bf16 v[122:125], v[160:163], v[184:187], v[122:125]
	v_mfma_f32_16x16x32_bf16 v[118:121], v[152:155], v[192:195], v[118:121]
	v_mfma_f32_16x16x32_bf16 v[114:117], v[160:163], v[192:195], v[114:117]
	v_mfma_f32_16x16x32_bf16 v[102:105], v[152:155], v[200:203], v[102:105]
	v_mfma_f32_16x16x32_bf16 v[98:101], v[160:163], v[200:203], v[98:101]
	v_mfma_f32_16x16x32_bf16 v[86:89], v[152:155], v[208:211], v[86:89]
	v_mfma_f32_16x16x32_bf16 v[82:85], v[160:163], v[208:211], v[82:85]
	v_mfma_f32_16x16x32_bf16 v[126:129], v[156:159], v[188:191], v[126:129]
	v_mfma_f32_16x16x32_bf16 v[122:125], v[164:167], v[188:191], v[122:125]
	v_mfma_f32_16x16x32_bf16 v[118:121], v[156:159], v[196:199], v[118:121]
	v_mfma_f32_16x16x32_bf16 v[114:117], v[164:167], v[196:199], v[114:117]
	v_mfma_f32_16x16x32_bf16 v[102:105], v[156:159], v[204:207], v[102:105]
	v_mfma_f32_16x16x32_bf16 v[98:101], v[164:167], v[204:207], v[98:101]
	v_mfma_f32_16x16x32_bf16 v[86:89], v[156:159], v[212:215], v[86:89]
	v_mfma_f32_16x16x32_bf16 v[82:85], v[164:167], v[212:215], v[82:85]
	s_setprio 0
	s_setprio 1
	v_mfma_f32_16x16x32_bf16 v[110:113], v[168:171], v[184:187], v[110:113]
	v_mfma_f32_16x16x32_bf16 v[106:109], v[176:179], v[184:187], v[106:109]
	v_mfma_f32_16x16x32_bf16 v[94:97], v[168:171], v[192:195], v[94:97]
	v_mfma_f32_16x16x32_bf16 v[90:93], v[176:179], v[192:195], v[90:93]
	v_mfma_f32_16x16x32_bf16 v[78:81], v[168:171], v[200:203], v[78:81]
	v_mfma_f32_16x16x32_bf16 v[74:77], v[176:179], v[200:203], v[74:77]
	v_mfma_f32_16x16x32_bf16 v[70:73], v[168:171], v[208:211], v[70:73]
	v_mfma_f32_16x16x32_bf16 v[66:69], v[176:179], v[208:211], v[66:69]
	v_mfma_f32_16x16x32_bf16 v[110:113], v[172:175], v[188:191], v[110:113]
	v_mfma_f32_16x16x32_bf16 v[106:109], v[180:183], v[188:191], v[106:109]
	v_mfma_f32_16x16x32_bf16 v[94:97], v[172:175], v[196:199], v[94:97]
	v_mfma_f32_16x16x32_bf16 v[90:93], v[180:183], v[196:199], v[90:93]
	v_mfma_f32_16x16x32_bf16 v[78:81], v[172:175], v[204:207], v[78:81]
	v_mfma_f32_16x16x32_bf16 v[74:77], v[180:183], v[204:207], v[74:77]
	v_mfma_f32_16x16x32_bf16 v[70:73], v[172:175], v[212:215], v[70:73]
	v_mfma_f32_16x16x32_bf16 v[66:69], v[180:183], v[212:215], v[66:69]
	s_setprio 0
	s_barrier
	s_add_i32 s66, s57, s35
	v_lshl_add_u64 v[216:217], s[22:23], 0, v[134:135]
	s_mov_b32 m0, s66
	ds_read_b128 v[184:187], v151 offset:16384
	ds_read_b128 v[188:191], v151 offset:17408
	ds_read_b128 v[192:195], v151 offset:18432
	ds_read_b128 v[196:199], v151 offset:19456
	ds_read_b128 v[200:203], v151 offset:20480
	ds_read_b128 v[204:207], v151 offset:21504
	ds_read_b128 v[208:211], v151 offset:22528
	ds_read_b128 v[212:215], v151 offset:23552
	global_load_lds_dwordx4 v[216:217], off
	s_add_i32 m0, s66, 0x2000
	s_add_u32 s66, s22, 0x40000
	v_lshl_add_u64 v[218:219], s[22:23], 0, v[130:131]
	s_addc_u32 s67, s23, 0
	s_add_i32 s68, s58, s35
	global_load_lds_dwordx4 v[218:219], off
	v_lshl_add_u64 v[220:221], s[66:67], 0, v[134:135]
	s_mov_b32 m0, s68
	v_lshl_add_u64 v[222:223], s[28:29], 0, v[132:133]
	global_load_lds_dwordx4 v[220:221], off
	v_lshl_add_u64 v[220:221], s[66:67], 0, v[130:131]
	s_add_i32 m0, s68, 0x2000
	s_nop 0
	global_load_lds_dwordx4 v[220:221], off
	v_lshl_add_u64 v[220:221], s[28:29], 0, v[136:137]
	s_mov_b32 m0, s11
	s_nop 0
	global_load_lds_dwordx4 v[220:221], off
	s_mov_b32 m0, s38
	s_nop 0
	global_load_lds_dwordx4 v[222:223], off
	s_waitcnt vmcnt(8)
	s_waitcnt lgkmcnt(0)
	s_barrier
; #define PG8_STAGE(bufoff, gbase, voff) do { _Pragma("unroll") for (int _i = 0; _i < 2; ++_i) \
;         __builtin_amdgcn_global_load_lds((const unsigned*)((const char*)(gbase) + (voff)[_i]), (LAS unsigned*)(lds + (bufoff) + ldsw + _i * 8192), 16, 0, 0); } while (0)
; #define PG8_LDA(dst, b, h) do { _Pragma("unroll") for (int m = 0; m < 4; ++m) _Pragma("unroll") for (int k = 0; k < 2; ++k) dst[m][k] = *(const LAS bf16x8*)(lds + PG8_SA(b, h) + aoff + m * 2048 + k * 1024); } while (0)
; #define PG8_LDB(dst, b, h) do { _Pragma("unroll") for (int n = 0; n < 2; ++n) _Pragma("unroll") for (int k = 0; k < 2; ++k) dst[n][k] = *(const LAS bf16x8*)(lds + PG8_SB(b, h) + boff + n * 2048 + k * 1024); } while (0)
; #define PG8_MMA(ai, bj, At, Bt) do { __builtin_amdgcn_s_setprio(1); _Pragma("unroll") for (int m = 0; m < 4; ++m) _Pragma("unroll") for (int n = 0; n < 2; ++n) _Pragma("unroll") for (int k = 0; k < 2; ++k) \
;         acc[ai][bj][m][n] = __builtin_amdgcn_mfma_f32_16x16x32_bf16(Bt[n][k], At[m][k], acc[ai][bj][m][n], 0, 0, 0); __builtin_amdgcn_s_setprio(0); } while (0)
; #define PG8_WAIT_V(n) asm volatile("s_waitcnt vmcnt(" #n ")" ::: "memory")
; #define PG8_WAIT_L(n) asm volatile("s_waitcnt lgkmcnt(" #n ")" ::: "memory")
; #define PG8_BAR __builtin_amdgcn_s_barrier()
; #define PG8_SCHED __builtin_amdgcn_sched_barrier(0)
; template <class Epi>
; __device__ __forceinline__ void gemm_phase(LAS unsigned char* lds, const Gemm g, const StaticOrder& S, const Epi& E) {
;     ...
;             PG8_WAIT_V(8); PG8_WAIT_L(0); PG8_BAR; PG8_MMA(1, 0, At, B0); PG8_MMA(1, 1, At, B1); PG8_BAR; PG8_SCHED;
;             PG8_LDB(B0, 1, 0); PG8_LDB(B1, 1, 1); PG8_SCHED; PG8_LDA(At, 1, 0); PG8_STAGE(PG8_SA(0, 1), a2 + hstep, voffA);
;             PG8_WAIT_V(8); PG8_WAIT_L(0); PG8_BAR; PG8_MMA(0, 0, At, B0); PG8_MMA(0, 1, At, B1); PG8_BAR; PG8_SCHED;
;             PG8_LDA(At, 1, 1); PG8_STAGE(PG8_SB(1, 0), b3, voffB); PG8_STAGE(PG8_SB(1, 1), b3 + hstep, voffB); PG8_STAGE(PG8_SA(1, 0), a3, voffA);
	s_setprio 1
	v_mfma_f32_16x16x32_bf16 v[62:65], v[152:155], v[184:187], v[62:65]
	v_mfma_f32_16x16x32_bf16 v[58:61], v[160:163], v[184:187], v[58:61]
	v_mfma_f32_16x16x32_bf16 v[54:57], v[152:155], v[192:195], v[54:57]
	v_mfma_f32_16x16x32_bf16 v[50:53], v[160:163], v[192:195], v[50:53]
	v_mfma_f32_16x16x32_bf16 v[38:41], v[152:155], v[200:203], v[38:41]
	v_mfma_f32_16x16x32_bf16 v[34:37], v[160:163], v[200:203], v[34:37]
	v_mfma_f32_16x16x32_bf16 v[22:25], v[152:155], v[208:211], v[22:25]
	v_mfma_f32_16x16x32_bf16 v[18:21], v[160:163], v[208:211], v[18:21]
	v_mfma_f32_16x16x32_bf16 v[62:65], v[156:159], v[188:191], v[62:65]
	v_mfma_f32_16x16x32_bf16 v[58:61], v[164:167], v[188:191], v[58:61]
	v_mfma_f32_16x16x32_bf16 v[54:57], v[156:159], v[196:199], v[54:57]
	v_mfma_f32_16x16x32_bf16 v[50:53], v[164:167], v[196:199], v[50:53]
	v_mfma_f32_16x16x32_bf16 v[38:41], v[156:159], v[204:207], v[38:41]
	v_mfma_f32_16x16x32_bf16 v[34:37], v[164:167], v[204:207], v[34:37]
	v_mfma_f32_16x16x32_bf16 v[22:25], v[156:159], v[212:215], v[22:25]
	v_mfma_f32_16x16x32_bf16 v[18:21], v[164:167], v[212:215], v[18:21]
	s_setprio 0
	s_setprio 1
	v_mfma_f32_16x16x32_bf16 v[46:49], v[168:171], v[184:187], v[46:49]
	v_mfma_f32_16x16x32_bf16 v[42:45], v[176:179], v[184:187], v[42:45]
	v_mfma_f32_16x16x32_bf16 v[30:33], v[168:171], v[192:195], v[30:33]
	v_mfma_f32_16x16x32_bf16 v[26:29], v[176:179], v[192:195], v[26:29]
	v_mfma_f32_16x16x32_bf16 v[14:17], v[168:171], v[200:203], v[14:17]
	v_mfma_f32_16x16x32_bf16 v[10:13], v[176:179], v[200:203], v[10:13]
	v_mfma_f32_16x16x32_bf16 v[6:9], v[168:171], v[208:211], v[6:9]
	v_mfma_f32_16x16x32_bf16 v[2:5], v[176:179], v[208:211], v[2:5]
	v_mfma_f32_16x16x32_bf16 v[46:49], v[172:175], v[188:191], v[46:49]
	v_mfma_f32_16x16x32_bf16 v[42:45], v[180:183], v[188:191], v[42:45]
	v_mfma_f32_16x16x32_bf16 v[30:33], v[172:175], v[196:199], v[30:33]
	v_mfma_f32_16x16x32_bf16 v[26:29], v[180:183], v[196:199], v[26:29]
	v_mfma_f32_16x16x32_bf16 v[14:17], v[172:175], v[204:207], v[14:17]
	v_mfma_f32_16x16x32_bf16 v[10:13], v[180:183], v[204:207], v[10:13]
	v_mfma_f32_16x16x32_bf16 v[6:9], v[172:175], v[212:215], v[6:9]
	v_mfma_f32_16x16x32_bf16 v[2:5], v[180:183], v[212:215], v[2:5]
	s_setprio 0
	s_barrier
	s_add_i32 s66, 0, 0x18000
	s_add_i32 s67, 0, 0x1c000
	v_add_u32_e32 v164, s66, v147
	v_add_u32_e32 v180, s67, v147
	ds_read_b128 v[152:155], v164
	ds_read_b128 v[156:159], v164 offset:1024
	ds_read_b128 v[160:163], v164 offset:2048
	ds_read_b128 v[164:167], v164 offset:3072
	ds_read_b128 v[168:171], v180
	ds_read_b128 v[172:175], v180 offset:1024
	ds_read_b128 v[176:179], v180 offset:2048
	ds_read_b128 v[180:183], v180 offset:3072
	s_add_u32 s28, s28, 0x40000
	s_addc_u32 s29, s29, 0
	s_mov_b32 m0, s39
	v_lshl_add_u64 v[224:225], s[28:29], 0, v[136:137]
	ds_read_b128 v[184:187], v151 offset:32768
	ds_read_b128 v[188:191], v151 offset:33792
	ds_read_b128 v[192:195], v151 offset:34816
	ds_read_b128 v[196:199], v151 offset:35840
	ds_read_b128 v[200:203], v151 offset:36864
	ds_read_b128 v[204:207], v151 offset:37888
	ds_read_b128 v[208:211], v151 offset:38912
	ds_read_b128 v[212:215], v151 offset:39936
	global_load_lds_dwordx4 v[224:225], off
	v_lshl_add_u64 v[224:225], s[28:29], 0, v[132:133]
	s_mov_b32 m0, s52
	s_nop 0
	global_load_lds_dwordx4 v[224:225], off
	s_waitcnt vmcnt(8)
	s_waitcnt lgkmcnt(0)
	s_barrier
	s_setprio 1
	v_mfma_f32_16x16x32_bf16 v[126:129], v[152:155], v[184:187], v[126:129]
	v_mfma_f32_16x16x32_bf16 v[122:125], v[160:163], v[184:187], v[122:125]
	v_mfma_f32_16x16x32_bf16 v[118:121], v[152:155], v[192:195], v[118:121]
	v_mfma_f32_16x16x32_bf16 v[114:117], v[160:163], v[192:195], v[114:117]
	v_mfma_f32_16x16x32_bf16 v[102:105], v[152:155], v[200:203], v[102:105]
	v_mfma_f32_16x16x32_bf16 v[98:101], v[160:163], v[200:203], v[98:101]
	v_mfma_f32_16x16x32_bf16 v[86:89], v[152:155], v[208:211], v[86:89]
	v_mfma_f32_16x16x32_bf16 v[82:85], v[160:163], v[208:211], v[82:85]
	v_mfma_f32_16x16x32_bf16 v[126:129], v[156:159], v[188:191], v[126:129]
	v_mfma_f32_16x16x32_bf16 v[122:125], v[164:167], v[188:191], v[122:125]
	v_mfma_f32_16x16x32_bf16 v[118:121], v[156:159], v[196:199], v[118:121]
	v_mfma_f32_16x16x32_bf16 v[114:117], v[164:167], v[196:199], v[114:117]
	v_mfma_f32_16x16x32_bf16 v[102:105], v[156:159], v[204:207], v[102:105]
	v_mfma_f32_16x16x32_bf16 v[98:101], v[164:167], v[204:207], v[98:101]
	v_mfma_f32_16x16x32_bf16 v[86:89], v[156:159], v[212:215], v[86:89]
	v_mfma_f32_16x16x32_bf16 v[82:85], v[164:167], v[212:215], v[82:85]
	s_setprio 0
	s_setprio 1
	v_mfma_f32_16x16x32_bf16 v[110:113], v[168:171], v[184:187], v[110:113]
	v_mfma_f32_16x16x32_bf16 v[106:109], v[176:179], v[184:187], v[106:109]
	v_mfma_f32_16x16x32_bf16 v[94:97], v[168:171], v[192:195], v[94:97]
	v_mfma_f32_16x16x32_bf16 v[90:93], v[176:179], v[192:195], v[90:93]
	v_mfma_f32_16x16x32_bf16 v[78:81], v[168:171], v[200:203], v[78:81]
	v_mfma_f32_16x16x32_bf16 v[74:77], v[176:179], v[200:203], v[74:77]
	v_mfma_f32_16x16x32_bf16 v[70:73], v[168:171], v[208:211], v[70:73]
	v_mfma_f32_16x16x32_bf16 v[66:69], v[176:179], v[208:211], v[66:69]
	v_mfma_f32_16x16x32_bf16 v[110:113], v[172:175], v[188:191], v[110:113]
	v_mfma_f32_16x16x32_bf16 v[106:109], v[180:183], v[188:191], v[106:109]
	v_mfma_f32_16x16x32_bf16 v[94:97], v[172:175], v[196:199], v[94:97]
	v_mfma_f32_16x16x32_bf16 v[90:93], v[180:183], v[196:199], v[90:93]
	v_mfma_f32_16x16x32_bf16 v[78:81], v[172:175], v[204:207], v[78:81]
	v_mfma_f32_16x16x32_bf16 v[74:77], v[180:183], v[204:207], v[74:77]
	v_mfma_f32_16x16x32_bf16 v[70:73], v[172:175], v[212:215], v[70:73]
	v_mfma_f32_16x16x32_bf16 v[66:69], v[180:183], v[212:215], v[66:69]
	s_setprio 0
	s_barrier
; #define PG8_STAGE(bufoff, gbase, voff) do { _Pragma("unroll") for (int _i = 0; _i < 2; ++_i) \
;         __builtin_amdgcn_global_load_lds((const unsigned*)((const char*)(gbase) + (voff)[_i]), (LAS unsigned*)(lds + (bufoff) + ldsw + _i * 8192), 16, 0, 0); } while (0)
; #define PG8_LDA(dst, b, h) do { _Pragma("unroll") for (int m = 0; m < 4; ++m) _Pragma("unroll") for (int k = 0; k < 2; ++k) dst[m][k] = *(const LAS bf16x8*)(lds + PG8_SA(b, h) + aoff + m * 2048 + k * 1024); } while (0)
; #define PG8_MMA(ai, bj, At, Bt) do { __builtin_amdgcn_s_setprio(1); _Pragma("unroll") for (int m = 0; m < 4; ++m) _Pragma("unroll") for (int n = 0; n < 2; ++n) _Pragma("unroll") for (int k = 0; k < 2; ++k) \
;         acc[ai][bj][m][n] = __builtin_amdgcn_mfma_f32_16x16x32_bf16(Bt[n][k], At[m][k], acc[ai][bj][m][n], 0, 0, 0); __builtin_amdgcn_s_setprio(0); } while (0)
; #define PG8_WAIT_V(n) asm volatile("s_waitcnt vmcnt(" #n ")" ::: "memory")
; #define PG8_WAIT_L(n) asm volatile("s_waitcnt lgkmcnt(" #n ")" ::: "memory")
; #define PG8_BAR __builtin_amdgcn_s_barrier()
; #define PG8_SCHED __builtin_amdgcn_sched_barrier(0)
; template <class Epi>
; __device__ __forceinline__ void gemm_phase(LAS unsigned char* lds, const Gemm g, const StaticOrder& S, const Epi& E) {
;     ...
;             PG8_LDA(At, 1, 1); PG8_STAGE(PG8_SB(1, 0), b3, voffB); PG8_STAGE(PG8_SB(1, 1), b3 + hstep, voffB); PG8_STAGE(PG8_SA(1, 0), a3, voffA);
;             PG8_WAIT_V(8); PG8_WAIT_L(0); PG8_BAR; PG8_MMA(1, 0, At, B0); PG8_MMA(1, 1, At, B1); PG8_BAR; PG8_SCHED;
;         }
	s_add_i32 s28, s66, s35
	v_lshl_add_u64 v[216:217], v[216:217], 0, s[6:7]
	s_mov_b32 m0, s28
	ds_read_b128 v[184:187], v151 offset:49152
	ds_read_b128 v[188:191], v151 offset:50176
	ds_read_b128 v[192:195], v151 offset:51200
	ds_read_b128 v[196:199], v151 offset:52224
	ds_read_b128 v[200:203], v151 offset:53248
	ds_read_b128 v[204:207], v151 offset:54272
	ds_read_b128 v[208:211], v151 offset:55296
	ds_read_b128 v[212:215], v151 offset:56320
	global_load_lds_dwordx4 v[216:217], off
	s_add_i32 m0, s28, 0x2000
	s_add_u32 s22, s22, 0x40080
	v_lshl_add_u64 v[216:217], v[218:219], 0, s[6:7]
	s_addc_u32 s23, s23, 0
	s_add_i32 s28, s67, s35
	global_load_lds_dwordx4 v[216:217], off
	v_lshl_add_u64 v[216:217], s[22:23], 0, v[134:135]
	s_mov_b32 m0, s28
	s_nop 0
	global_load_lds_dwordx4 v[216:217], off
	v_lshl_add_u64 v[216:217], s[22:23], 0, v[130:131]
	s_add_i32 m0, s28, 0x2000
	s_nop 0
	global_load_lds_dwordx4 v[216:217], off
	v_lshl_add_u64 v[216:217], v[220:221], 0, s[6:7]
	s_mov_b32 m0, s54
	s_nop 0
	global_load_lds_dwordx4 v[216:217], off
	v_lshl_add_u64 v[216:217], v[222:223], 0, s[6:7]
	s_mov_b32 m0, s55
	s_nop 0
	global_load_lds_dwordx4 v[216:217], off
	s_waitcnt vmcnt(8)
	s_waitcnt lgkmcnt(0)
	s_barrier
	s_setprio 1
	v_mfma_f32_16x16x32_bf16 v[62:65], v[152:155], v[184:187], v[62:65]
	v_mfma_f32_16x16x32_bf16 v[58:61], v[160:163], v[184:187], v[58:61]
	v_mfma_f32_16x16x32_bf16 v[54:57], v[152:155], v[192:195], v[54:57]
	v_mfma_f32_16x16x32_bf16 v[50:53], v[160:163], v[192:195], v[50:53]
	v_mfma_f32_16x16x32_bf16 v[38:41], v[152:155], v[200:203], v[38:41]
	v_mfma_f32_16x16x32_bf16 v[34:37], v[160:163], v[200:203], v[34:37]
	v_mfma_f32_16x16x32_bf16 v[22:25], v[152:155], v[208:211], v[22:25]
	v_mfma_f32_16x16x32_bf16 v[18:21], v[160:163], v[208:211], v[18:21]
	v_mfma_f32_16x16x32_bf16 v[62:65], v[156:159], v[188:191], v[62:65]
	v_mfma_f32_16x16x32_bf16 v[58:61], v[164:167], v[188:191], v[58:61]
	v_mfma_f32_16x16x32_bf16 v[54:57], v[156:159], v[196:199], v[54:57]
	v_mfma_f32_16x16x32_bf16 v[50:53], v[164:167], v[196:199], v[50:53]
	v_mfma_f32_16x16x32_bf16 v[38:41], v[156:159], v[204:207], v[38:41]
	v_mfma_f32_16x16x32_bf16 v[34:37], v[164:167], v[204:207], v[34:37]
	v_mfma_f32_16x16x32_bf16 v[22:25], v[156:159], v[212:215], v[22:25]
	v_mfma_f32_16x16x32_bf16 v[18:21], v[164:167], v[212:215], v[18:21]
	s_setprio 0
	s_setprio 1
	v_mfma_f32_16x16x32_bf16 v[46:49], v[168:171], v[184:187], v[46:49]
	v_mfma_f32_16x16x32_bf16 v[42:45], v[176:179], v[184:187], v[42:45]
	v_mfma_f32_16x16x32_bf16 v[30:33], v[168:171], v[192:195], v[30:33]
	v_mfma_f32_16x16x32_bf16 v[26:29], v[176:179], v[192:195], v[26:29]
	v_mfma_f32_16x16x32_bf16 v[14:17], v[168:171], v[200:203], v[14:17]
	v_mfma_f32_16x16x32_bf16 v[10:13], v[176:179], v[200:203], v[10:13]
	v_mfma_f32_16x16x32_bf16 v[6:9], v[168:171], v[208:211], v[6:9]
	v_mfma_f32_16x16x32_bf16 v[2:5], v[176:179], v[208:211], v[2:5]
	v_mfma_f32_16x16x32_bf16 v[46:49], v[172:175], v[188:191], v[46:49]
	v_mfma_f32_16x16x32_bf16 v[42:45], v[180:183], v[188:191], v[42:45]
	v_mfma_f32_16x16x32_bf16 v[30:33], v[172:175], v[196:199], v[30:33]
	v_mfma_f32_16x16x32_bf16 v[26:29], v[180:183], v[196:199], v[26:29]
	v_mfma_f32_16x16x32_bf16 v[14:17], v[172:175], v[204:207], v[14:17]
	v_mfma_f32_16x16x32_bf16 v[10:13], v[180:183], v[204:207], v[10:13]
	v_mfma_f32_16x16x32_bf16 v[6:9], v[172:175], v[212:215], v[6:9]
	v_mfma_f32_16x16x32_bf16 v[2:5], v[180:183], v[212:215], v[2:5]
	s_setprio 0
	s_barrier
	s_add_i32 s65, s65, 2
	s_add_u32 s20, s20, 0x100
	s_addc_u32 s21, s21, 0
	s_add_u32 s63, s63, 0x100
	s_addc_u32 s64, s64, 0
	s_cmp_gt_u32 s65, 13
	s_cbranch_scc0 .LBB0_314
	s_and_b64 vcc, exec, s[8:9]
	s_cbranch_vccz .LBB0_317
	s_barrier

; #define PG8_STAGE(bufoff, gbase, voff) do { _Pragma("unroll") for (int _i = 0; _i < 2; ++_i) \
;         __builtin_amdgcn_global_load_lds((const unsigned*)((const char*)(gbase) + (voff)[_i]), (LAS unsigned*)(lds + (bufoff) + ldsw + _i * 8192), 16, 0, 0); } while (0)
; #define PG8_LDA(dst, b, h) do { _Pragma("unroll") for (int m = 0; m < 4; ++m) _Pragma("unroll") for (int k = 0; k < 2; ++k) dst[m][k] = *(const LAS bf16x8*)(lds + PG8_SA(b, h) + aoff + m * 2048 + k * 1024); } while (0)
; #define PG8_LDB(dst, b, h) do { _Pragma("unroll") for (int n = 0; n < 2; ++n) _Pragma("unroll") for (int k = 0; k < 2; ++k) dst[n][k] = *(const LAS bf16x8*)(lds + PG8_SB(b, h) + boff + n * 2048 + k * 1024); } while (0)
; #define PG8_MMA(ai, bj, At, Bt) do { __builtin_amdgcn_s_setprio(1); _Pragma("unroll") for (int m = 0; m < 4; ++m) _Pragma("unroll") for (int n = 0; n < 2; ++n) _Pragma("unroll") for (int k = 0; k < 2; ++k) \
;         acc[ai][bj][m][n] = __builtin_amdgcn_mfma_f32_16x16x32_bf16(Bt[n][k], At[m][k], acc[ai][bj][m][n], 0, 0, 0); __builtin_amdgcn_s_setprio(0); } while (0)
; #define PG8_WAIT_V(n) asm volatile("s_waitcnt vmcnt(" #n ")" ::: "memory")
; #define PG8_WAIT_L(n) asm volatile("s_waitcnt lgkmcnt(" #n ")" ::: "memory")
; #define PG8_BAR __builtin_amdgcn_s_barrier()
; #define PG8_SCHED __builtin_amdgcn_sched_barrier(0)
; template <class Epi>
; __device__ __forceinline__ void gemm_phase(LAS unsigned char* lds, const Gemm g, const StaticOrder& S, const Epi& E) {
;     ...
;             PG8_LDB(B0, 0, 0); PG8_LDB(B1, 0, 1); PG8_SCHED; PG8_LDA(At, 0, 0); PG8_STAGE(PG8_SA(1, 1), a1 + hstep, voffA);
;             PG8_WAIT_V(8); PG8_WAIT_L(0); PG8_BAR; PG8_MMA(0, 0, At, B0); PG8_MMA(0, 1, At, B1); PG8_BAR; PG8_SCHED;
;             PG8_LDA(At, 0, 1); PG8_STAGE(PG8_SB(0, 0), b2, voffB); PG8_STAGE(PG8_SB(0, 1), b2 + hstep, voffB); PG8_STAGE(PG8_SA(0, 0), a2, voffA);
;             PG8_WAIT_V(8); PG8_WAIT_L(0); PG8_BAR; PG8_MMA(1, 0, At, B0); PG8_MMA(1, 1, At, B1); PG8_BAR; PG8_SCHED;
.LBB0_716:
	ds_read_b128 v[142:145], v151
	ds_read_b128 v[154:157], v151 offset:1024
	ds_read_b128 v[158:161], v151 offset:2048
	ds_read_b128 v[162:165], v151 offset:3072
	ds_read_b128 v[166:169], v152
	ds_read_b128 v[170:173], v152 offset:1024
	ds_read_b128 v[174:177], v152 offset:2048
	ds_read_b128 v[178:181], v152 offset:3072
	s_add_u32 s30, s28, 0xfffc0080
	s_addc_u32 s31, s29, -1
	s_cmp_eq_u32 s58, 12
	s_cselect_b32 s35, s21, s31
	s_cselect_b32 s34, s54, s30
	s_cselect_b32 s31, s19, s57
	s_cselect_b32 s30, s55, s56
	v_lshl_add_u64 v[146:147], s[28:29], 0, v[134:135]
	s_add_i32 m0, s40, 0xc000
	ds_read_b128 v[182:185], v153
	ds_read_b128 v[186:189], v153 offset:1024
	ds_read_b128 v[190:193], v153 offset:2048
	ds_read_b128 v[194:197], v153 offset:3072
	ds_read_b128 v[198:201], v153 offset:4096
	ds_read_b128 v[202:205], v153 offset:5120
	ds_read_b128 v[206:209], v153 offset:6144
	ds_read_b128 v[210:213], v153 offset:7168
	global_load_lds_dwordx4 v[146:147], off
	v_lshl_add_u64 v[146:147], s[28:29], 0, v[136:137]
	s_add_i32 m0, s40, 0xe000
	s_nop 0
	global_load_lds_dwordx4 v[146:147], off
	s_waitcnt vmcnt(8)
	s_waitcnt lgkmcnt(0)
	s_barrier
	s_setprio 1
	v_mfma_f32_16x16x32_bf16 v[126:129], v[142:145], v[182:185], v[126:129]
	v_mfma_f32_16x16x32_bf16 v[122:125], v[158:161], v[182:185], v[122:125]
	v_mfma_f32_16x16x32_bf16 v[114:117], v[142:145], v[190:193], v[114:117]
	v_mfma_f32_16x16x32_bf16 v[106:109], v[158:161], v[190:193], v[106:109]
	v_mfma_f32_16x16x32_bf16 v[94:97], v[142:145], v[198:201], v[94:97]
	v_mfma_f32_16x16x32_bf16 v[90:93], v[158:161], v[198:201], v[90:93]
	v_mfma_f32_16x16x32_bf16 v[78:81], v[142:145], v[206:209], v[78:81]
	v_mfma_f32_16x16x32_bf16 v[74:77], v[158:161], v[206:209], v[74:77]
	v_mfma_f32_16x16x32_bf16 v[126:129], v[154:157], v[186:189], v[126:129]
	v_mfma_f32_16x16x32_bf16 v[122:125], v[162:165], v[186:189], v[122:125]
	v_mfma_f32_16x16x32_bf16 v[114:117], v[154:157], v[194:197], v[114:117]
	v_mfma_f32_16x16x32_bf16 v[106:109], v[162:165], v[194:197], v[106:109]
	v_mfma_f32_16x16x32_bf16 v[94:97], v[154:157], v[202:205], v[94:97]
	v_mfma_f32_16x16x32_bf16 v[90:93], v[162:165], v[202:205], v[90:93]
	v_mfma_f32_16x16x32_bf16 v[78:81], v[154:157], v[210:213], v[78:81]
	v_mfma_f32_16x16x32_bf16 v[74:77], v[162:165], v[210:213], v[74:77]
	s_setprio 0
	s_setprio 1
	v_mfma_f32_16x16x32_bf16 v[118:121], v[166:169], v[182:185], v[118:121]
	v_mfma_f32_16x16x32_bf16 v[110:113], v[174:177], v[182:185], v[110:113]
	v_mfma_f32_16x16x32_bf16 v[102:105], v[166:169], v[190:193], v[102:105]
	v_mfma_f32_16x16x32_bf16 v[98:101], v[174:177], v[190:193], v[98:101]
	v_mfma_f32_16x16x32_bf16 v[86:89], v[166:169], v[198:201], v[86:89]
	v_mfma_f32_16x16x32_bf16 v[82:85], v[174:177], v[198:201], v[82:85]
	v_mfma_f32_16x16x32_bf16 v[70:73], v[166:169], v[206:209], v[70:73]
	v_mfma_f32_16x16x32_bf16 v[66:69], v[174:177], v[206:209], v[66:69]
	v_mfma_f32_16x16x32_bf16 v[118:121], v[170:173], v[186:189], v[118:121]
	v_mfma_f32_16x16x32_bf16 v[110:113], v[178:181], v[186:189], v[110:113]
	v_mfma_f32_16x16x32_bf16 v[102:105], v[170:173], v[194:197], v[102:105]
	v_mfma_f32_16x16x32_bf16 v[98:101], v[178:181], v[194:197], v[98:101]
	v_mfma_f32_16x16x32_bf16 v[86:89], v[170:173], v[202:205], v[86:89]
	v_mfma_f32_16x16x32_bf16 v[82:85], v[178:181], v[202:205], v[82:85]
	v_mfma_f32_16x16x32_bf16 v[70:73], v[170:173], v[210:213], v[70:73]
	v_mfma_f32_16x16x32_bf16 v[66:69], v[178:181], v[210:213], v[66:69]
	s_setprio 0
	s_barrier
	s_add_i32 s59, s48, s39
	v_lshl_add_u64 v[146:147], s[30:31], 0, v[130:131]
	s_mov_b32 m0, s59
	ds_read_b128 v[182:185], v153 offset:16384
	ds_read_b128 v[186:189], v153 offset:17408
	ds_read_b128 v[190:193], v153 offset:18432
	ds_read_b128 v[194:197], v153 offset:19456
	ds_read_b128 v[198:201], v153 offset:20480
	ds_read_b128 v[202:205], v153 offset:21504
	ds_read_b128 v[206:209], v153 offset:22528
	ds_read_b128 v[210:213], v153 offset:23552
	global_load_lds_dwordx4 v[146:147], off
	s_add_i32 m0, s59, 0x2000
	s_add_u32 s60, s30, 0x40000
	v_lshl_add_u64 v[214:215], s[30:31], 0, v[132:133]
	s_addc_u32 s61, s31, 0
	s_add_i32 s59, s49, s39
	global_load_lds_dwordx4 v[214:215], off
	v_lshl_add_u64 v[216:217], s[60:61], 0, v[130:131]
	s_mov_b32 m0, s59
	v_lshl_add_u64 v[218:219], s[34:35], 0, v[132:133]
	global_load_lds_dwordx4 v[216:217], off
	v_lshl_add_u64 v[216:217], s[60:61], 0, v[132:133]
	s_add_i32 m0, s59, 0x2000
	s_nop 0
	global_load_lds_dwordx4 v[216:217], off
	v_lshl_add_u64 v[216:217], s[34:35], 0, v[130:131]
	s_mov_b32 m0, s40
	s_nop 0
	global_load_lds_dwordx4 v[216:217], off
	s_mov_b32 m0, s41
	s_nop 0
	global_load_lds_dwordx4 v[218:219], off
	s_waitcnt vmcnt(8)
	s_waitcnt lgkmcnt(0)
	s_barrier
; #define PG8_STAGE(bufoff, gbase, voff) do { _Pragma("unroll") for (int _i = 0; _i < 2; ++_i) \
;         __builtin_amdgcn_global_load_lds((const unsigned*)((const char*)(gbase) + (voff)[_i]), (LAS unsigned*)(lds + (bufoff) + ldsw + _i * 8192), 16, 0, 0); } while (0)
; #define PG8_LDA(dst, b, h) do { _Pragma("unroll") for (int m = 0; m < 4; ++m) _Pragma("unroll") for (int k = 0; k < 2; ++k) dst[m][k] = *(const LAS bf16x8*)(lds + PG8_SA(b, h) + aoff + m * 2048 + k * 1024); } while (0)
; #define PG8_LDB(dst, b, h) do { _Pragma("unroll") for (int n = 0; n < 2; ++n) _Pragma("unroll") for (int k = 0; k < 2; ++k) dst[n][k] = *(const LAS bf16x8*)(lds + PG8_SB(b, h) + boff + n * 2048 + k * 1024); } while (0)
; #define PG8_MMA(ai, bj, At, Bt) do { __builtin_amdgcn_s_setprio(1); _Pragma("unroll") for (int m = 0; m < 4; ++m) _Pragma("unroll") for (int n = 0; n < 2; ++n) _Pragma("unroll") for (int k = 0; k < 2; ++k) \
;         acc[ai][bj][m][n] = __builtin_amdgcn_mfma_f32_16x16x32_bf16(Bt[n][k], At[m][k], acc[ai][bj][m][n], 0, 0, 0); __builtin_amdgcn_s_setprio(0); } while (0)
; #define PG8_WAIT_V(n) asm volatile("s_waitcnt vmcnt(" #n ")" ::: "memory")
; #define PG8_WAIT_L(n) asm volatile("s_waitcnt lgkmcnt(" #n ")" ::: "memory")
; #define PG8_BAR __builtin_amdgcn_s_barrier()
; #define PG8_SCHED __builtin_amdgcn_sched_barrier(0)
; template <class Epi>
; __device__ __forceinline__ void gemm_phase(LAS unsigned char* lds, const Gemm g, const StaticOrder& S, const Epi& E) {
;     ...
;             PG8_WAIT_V(8); PG8_WAIT_L(0); PG8_BAR; PG8_MMA(1, 0, At, B0); PG8_MMA(1, 1, At, B1); PG8_BAR; PG8_SCHED;
;             PG8_LDB(B0, 1, 0); PG8_LDB(B1, 1, 1); PG8_SCHED; PG8_LDA(At, 1, 0); PG8_STAGE(PG8_SA(0, 1), a2 + hstep, voffA);
;             PG8_WAIT_V(8); PG8_WAIT_L(0); PG8_BAR; PG8_MMA(0, 0, At, B0); PG8_MMA(0, 1, At, B1); PG8_BAR; PG8_SCHED;
;             PG8_LDA(At, 1, 1); PG8_STAGE(PG8_SB(1, 0), b3, voffB); PG8_STAGE(PG8_SB(1, 1), b3 + hstep, voffB); PG8_STAGE(PG8_SA(1, 0), a3, voffA);
	s_setprio 1
	v_mfma_f32_16x16x32_bf16 v[62:65], v[142:145], v[182:185], v[62:65]
	v_mfma_f32_16x16x32_bf16 v[58:61], v[158:161], v[182:185], v[58:61]
	v_mfma_f32_16x16x32_bf16 v[46:49], v[142:145], v[190:193], v[46:49]
	v_mfma_f32_16x16x32_bf16 v[42:45], v[158:161], v[190:193], v[42:45]
	v_mfma_f32_16x16x32_bf16 v[30:33], v[142:145], v[198:201], v[30:33]
	v_mfma_f32_16x16x32_bf16 v[26:29], v[158:161], v[198:201], v[26:29]
	v_mfma_f32_16x16x32_bf16 v[14:17], v[142:145], v[206:209], v[14:17]
	v_mfma_f32_16x16x32_bf16 v[10:13], v[158:161], v[206:209], v[10:13]
	v_mfma_f32_16x16x32_bf16 v[62:65], v[154:157], v[186:189], v[62:65]
	v_mfma_f32_16x16x32_bf16 v[58:61], v[162:165], v[186:189], v[58:61]
	v_mfma_f32_16x16x32_bf16 v[46:49], v[154:157], v[194:197], v[46:49]
	v_mfma_f32_16x16x32_bf16 v[42:45], v[162:165], v[194:197], v[42:45]
	v_mfma_f32_16x16x32_bf16 v[30:33], v[154:157], v[202:205], v[30:33]
	v_mfma_f32_16x16x32_bf16 v[26:29], v[162:165], v[202:205], v[26:29]
	v_mfma_f32_16x16x32_bf16 v[14:17], v[154:157], v[210:213], v[14:17]
	v_mfma_f32_16x16x32_bf16 v[10:13], v[162:165], v[210:213], v[10:13]
	s_setprio 0
	s_setprio 1
	v_mfma_f32_16x16x32_bf16 v[54:57], v[166:169], v[182:185], v[54:57]
	v_mfma_f32_16x16x32_bf16 v[50:53], v[174:177], v[182:185], v[50:53]
	v_mfma_f32_16x16x32_bf16 v[38:41], v[166:169], v[190:193], v[38:41]
	v_mfma_f32_16x16x32_bf16 v[34:37], v[174:177], v[190:193], v[34:37]
	v_mfma_f32_16x16x32_bf16 v[22:25], v[166:169], v[198:201], v[22:25]
	v_mfma_f32_16x16x32_bf16 v[18:21], v[174:177], v[198:201], v[18:21]
	v_mfma_f32_16x16x32_bf16 v[6:9], v[166:169], v[206:209], v[6:9]
	v_mfma_f32_16x16x32_bf16 v[2:5], v[174:177], v[206:209], v[2:5]
	v_mfma_f32_16x16x32_bf16 v[54:57], v[170:173], v[186:189], v[54:57]
	v_mfma_f32_16x16x32_bf16 v[50:53], v[178:181], v[186:189], v[50:53]
	v_mfma_f32_16x16x32_bf16 v[38:41], v[170:173], v[194:197], v[38:41]
	v_mfma_f32_16x16x32_bf16 v[34:37], v[178:181], v[194:197], v[34:37]
	v_mfma_f32_16x16x32_bf16 v[22:25], v[170:173], v[202:205], v[22:25]
	v_mfma_f32_16x16x32_bf16 v[18:21], v[178:181], v[202:205], v[18:21]
	v_mfma_f32_16x16x32_bf16 v[6:9], v[170:173], v[210:213], v[6:9]
	v_mfma_f32_16x16x32_bf16 v[2:5], v[178:181], v[210:213], v[2:5]
	s_setprio 0
	s_barrier
	s_add_i32 s59, 0, 0x18000
	s_add_i32 s60, 0, 0x1c000
	v_add_u32_e32 v162, s59, v149
	v_add_u32_e32 v178, s60, v149
	ds_read_b128 v[142:145], v162
	ds_read_b128 v[154:157], v162 offset:1024
	ds_read_b128 v[158:161], v162 offset:2048
	ds_read_b128 v[162:165], v162 offset:3072
	ds_read_b128 v[166:169], v178
	ds_read_b128 v[170:173], v178 offset:1024
	ds_read_b128 v[174:177], v178 offset:2048
	ds_read_b128 v[178:181], v178 offset:3072
	s_add_u32 s34, s34, 0x40000
	s_addc_u32 s35, s35, 0
	s_mov_b32 m0, s42
	v_lshl_add_u64 v[220:221], s[34:35], 0, v[130:131]
	ds_read_b128 v[182:185], v153 offset:32768
	ds_read_b128 v[186:189], v153 offset:33792
	ds_read_b128 v[190:193], v153 offset:34816
	ds_read_b128 v[194:197], v153 offset:35840
	ds_read_b128 v[198:201], v153 offset:36864
	ds_read_b128 v[202:205], v153 offset:37888
	ds_read_b128 v[206:209], v153 offset:38912
	ds_read_b128 v[210:213], v153 offset:39936
	global_load_lds_dwordx4 v[220:221], off
	v_lshl_add_u64 v[220:221], s[34:35], 0, v[132:133]
	s_mov_b32 m0, s43
	s_nop 0
	global_load_lds_dwordx4 v[220:221], off
	s_waitcnt vmcnt(8)
	s_waitcnt lgkmcnt(0)
	s_barrier
	s_setprio 1
	v_mfma_f32_16x16x32_bf16 v[126:129], v[142:145], v[182:185], v[126:129]
	v_mfma_f32_16x16x32_bf16 v[122:125], v[158:161], v[182:185], v[122:125]
	v_mfma_f32_16x16x32_bf16 v[114:117], v[142:145], v[190:193], v[114:117]
	v_mfma_f32_16x16x32_bf16 v[106:109], v[158:161], v[190:193], v[106:109]
	v_mfma_f32_16x16x32_bf16 v[94:97], v[142:145], v[198:201], v[94:97]
	v_mfma_f32_16x16x32_bf16 v[90:93], v[158:161], v[198:201], v[90:93]
	v_mfma_f32_16x16x32_bf16 v[78:81], v[142:145], v[206:209], v[78:81]
	v_mfma_f32_16x16x32_bf16 v[74:77], v[158:161], v[206:209], v[74:77]
	v_mfma_f32_16x16x32_bf16 v[126:129], v[154:157], v[186:189], v[126:129]
	v_mfma_f32_16x16x32_bf16 v[122:125], v[162:165], v[186:189], v[122:125]
	v_mfma_f32_16x16x32_bf16 v[114:117], v[154:157], v[194:197], v[114:117]
	v_mfma_f32_16x16x32_bf16 v[106:109], v[162:165], v[194:197], v[106:109]
	v_mfma_f32_16x16x32_bf16 v[94:97], v[154:157], v[202:205], v[94:97]
	v_mfma_f32_16x16x32_bf16 v[90:93], v[162:165], v[202:205], v[90:93]
	v_mfma_f32_16x16x32_bf16 v[78:81], v[154:157], v[210:213], v[78:81]
	v_mfma_f32_16x16x32_bf16 v[74:77], v[162:165], v[210:213], v[74:77]
	s_setprio 0
	s_setprio 1
	v_mfma_f32_16x16x32_bf16 v[118:121], v[166:169], v[182:185], v[118:121]
	v_mfma_f32_16x16x32_bf16 v[110:113], v[174:177], v[182:185], v[110:113]
	v_mfma_f32_16x16x32_bf16 v[102:105], v[166:169], v[190:193], v[102:105]
	v_mfma_f32_16x16x32_bf16 v[98:101], v[174:177], v[190:193], v[98:101]
	v_mfma_f32_16x16x32_bf16 v[86:89], v[166:169], v[198:201], v[86:89]
	v_mfma_f32_16x16x32_bf16 v[82:85], v[174:177], v[198:201], v[82:85]
	v_mfma_f32_16x16x32_bf16 v[70:73], v[166:169], v[206:209], v[70:73]
	v_mfma_f32_16x16x32_bf16 v[66:69], v[174:177], v[206:209], v[66:69]
	v_mfma_f32_16x16x32_bf16 v[118:121], v[170:173], v[186:189], v[118:121]
	v_mfma_f32_16x16x32_bf16 v[110:113], v[178:181], v[186:189], v[110:113]
	v_mfma_f32_16x16x32_bf16 v[102:105], v[170:173], v[194:197], v[102:105]
	v_mfma_f32_16x16x32_bf16 v[98:101], v[178:181], v[194:197], v[98:101]
	v_mfma_f32_16x16x32_bf16 v[86:89], v[170:173], v[202:205], v[86:89]
	v_mfma_f32_16x16x32_bf16 v[82:85], v[178:181], v[202:205], v[82:85]
	v_mfma_f32_16x16x32_bf16 v[70:73], v[170:173], v[210:213], v[70:73]
	v_mfma_f32_16x16x32_bf16 v[66:69], v[178:181], v[210:213], v[66:69]
	s_setprio 0
	s_barrier
; #define PG8_STAGE(bufoff, gbase, voff) do { _Pragma("unroll") for (int _i = 0; _i < 2; ++_i) \
;         __builtin_amdgcn_global_load_lds((const unsigned*)((const char*)(gbase) + (voff)[_i]), (LAS unsigned*)(lds + (bufoff) + ldsw + _i * 8192), 16, 0, 0); } while (0)
; #define PG8_LDA(dst, b, h) do { _Pragma("unroll") for (int m = 0; m < 4; ++m) _Pragma("unroll") for (int k = 0; k < 2; ++k) dst[m][k] = *(const LAS bf16x8*)(lds + PG8_SA(b, h) + aoff + m * 2048 + k * 1024); } while (0)
; #define PG8_MMA(ai, bj, At, Bt) do { __builtin_amdgcn_s_setprio(1); _Pragma("unroll") for (int m = 0; m < 4; ++m) _Pragma("unroll") for (int n = 0; n < 2; ++n) _Pragma("unroll") for (int k = 0; k < 2; ++k) \
;         acc[ai][bj][m][n] = __builtin_amdgcn_mfma_f32_16x16x32_bf16(Bt[n][k], At[m][k], acc[ai][bj][m][n], 0, 0, 0); __builtin_amdgcn_s_setprio(0); } while (0)
; #define PG8_WAIT_V(n) asm volatile("s_waitcnt vmcnt(" #n ")" ::: "memory")
; #define PG8_WAIT_L(n) asm volatile("s_waitcnt lgkmcnt(" #n ")" ::: "memory")
; #define PG8_BAR __builtin_amdgcn_s_barrier()
; #define PG8_SCHED __builtin_amdgcn_sched_barrier(0)
; template <class Epi>
; __device__ __forceinline__ void gemm_phase(LAS unsigned char* lds, const Gemm g, const StaticOrder& S, const Epi& E) {
;     ...
;             PG8_LDA(At, 1, 1); PG8_STAGE(PG8_SB(1, 0), b3, voffB); PG8_STAGE(PG8_SB(1, 1), b3 + hstep, voffB); PG8_STAGE(PG8_SA(1, 0), a3, voffA);
;             PG8_WAIT_V(8); PG8_WAIT_L(0); PG8_BAR; PG8_MMA(1, 0, At, B0); PG8_MMA(1, 1, At, B1); PG8_BAR; PG8_SCHED;
;         }
	s_add_i32 s34, s59, s39
	v_lshl_add_u64 v[146:147], v[146:147], 0, s[4:5]
	s_mov_b32 m0, s34
	ds_read_b128 v[182:185], v153 offset:49152
	ds_read_b128 v[186:189], v153 offset:50176
	ds_read_b128 v[190:193], v153 offset:51200
	ds_read_b128 v[194:197], v153 offset:52224
	ds_read_b128 v[198:201], v153 offset:53248
	ds_read_b128 v[202:205], v153 offset:54272
	ds_read_b128 v[206:209], v153 offset:55296
	ds_read_b128 v[210:213], v153 offset:56320
	global_load_lds_dwordx4 v[146:147], off
	s_add_i32 m0, s34, 0x2000
	s_add_u32 s30, s30, 0x40080
	v_lshl_add_u64 v[146:147], v[214:215], 0, s[4:5]
	s_addc_u32 s31, s31, 0
	s_add_i32 s34, s60, s39
	global_load_lds_dwordx4 v[146:147], off
	v_lshl_add_u64 v[146:147], s[30:31], 0, v[130:131]
	s_mov_b32 m0, s34
	s_nop 0
	global_load_lds_dwordx4 v[146:147], off
	v_lshl_add_u64 v[146:147], s[30:31], 0, v[132:133]
	s_add_i32 m0, s34, 0x2000
	s_nop 0
	global_load_lds_dwordx4 v[146:147], off
	v_lshl_add_u64 v[146:147], v[216:217], 0, s[4:5]
	s_mov_b32 m0, s45
	s_nop 0
	global_load_lds_dwordx4 v[146:147], off
	v_lshl_add_u64 v[146:147], v[218:219], 0, s[4:5]
	s_mov_b32 m0, s46
	s_nop 0
	global_load_lds_dwordx4 v[146:147], off
	s_waitcnt vmcnt(8)
	s_waitcnt lgkmcnt(0)
	s_barrier
	s_setprio 1
	v_mfma_f32_16x16x32_bf16 v[62:65], v[142:145], v[182:185], v[62:65]
	v_mfma_f32_16x16x32_bf16 v[58:61], v[158:161], v[182:185], v[58:61]
	v_mfma_f32_16x16x32_bf16 v[46:49], v[142:145], v[190:193], v[46:49]
	v_mfma_f32_16x16x32_bf16 v[42:45], v[158:161], v[190:193], v[42:45]
	v_mfma_f32_16x16x32_bf16 v[30:33], v[142:145], v[198:201], v[30:33]
	v_mfma_f32_16x16x32_bf16 v[26:29], v[158:161], v[198:201], v[26:29]
	v_mfma_f32_16x16x32_bf16 v[14:17], v[142:145], v[206:209], v[14:17]
	v_mfma_f32_16x16x32_bf16 v[10:13], v[158:161], v[206:209], v[10:13]
	v_mfma_f32_16x16x32_bf16 v[62:65], v[154:157], v[186:189], v[62:65]
	v_mfma_f32_16x16x32_bf16 v[58:61], v[162:165], v[186:189], v[58:61]
	v_mfma_f32_16x16x32_bf16 v[46:49], v[154:157], v[194:197], v[46:49]
	v_mfma_f32_16x16x32_bf16 v[42:45], v[162:165], v[194:197], v[42:45]
	v_mfma_f32_16x16x32_bf16 v[30:33], v[154:157], v[202:205], v[30:33]
	v_mfma_f32_16x16x32_bf16 v[26:29], v[162:165], v[202:205], v[26:29]
	v_mfma_f32_16x16x32_bf16 v[14:17], v[154:157], v[210:213], v[14:17]
	v_mfma_f32_16x16x32_bf16 v[10:13], v[162:165], v[210:213], v[10:13]
	s_setprio 0
	s_setprio 1
	v_mfma_f32_16x16x32_bf16 v[54:57], v[166:169], v[182:185], v[54:57]
	v_mfma_f32_16x16x32_bf16 v[50:53], v[174:177], v[182:185], v[50:53]
	v_mfma_f32_16x16x32_bf16 v[38:41], v[166:169], v[190:193], v[38:41]
	v_mfma_f32_16x16x32_bf16 v[34:37], v[174:177], v[190:193], v[34:37]
	v_mfma_f32_16x16x32_bf16 v[22:25], v[166:169], v[198:201], v[22:25]
	v_mfma_f32_16x16x32_bf16 v[18:21], v[174:177], v[198:201], v[18:21]
	v_mfma_f32_16x16x32_bf16 v[6:9], v[166:169], v[206:209], v[6:9]
	v_mfma_f32_16x16x32_bf16 v[2:5], v[174:177], v[206:209], v[2:5]
	v_mfma_f32_16x16x32_bf16 v[54:57], v[170:173], v[186:189], v[54:57]
	v_mfma_f32_16x16x32_bf16 v[50:53], v[178:181], v[186:189], v[50:53]
	v_mfma_f32_16x16x32_bf16 v[38:41], v[170:173], v[194:197], v[38:41]
	v_mfma_f32_16x16x32_bf16 v[34:37], v[178:181], v[194:197], v[34:37]
	v_mfma_f32_16x16x32_bf16 v[22:25], v[170:173], v[202:205], v[22:25]
	v_mfma_f32_16x16x32_bf16 v[18:21], v[178:181], v[202:205], v[18:21]
	v_mfma_f32_16x16x32_bf16 v[6:9], v[170:173], v[210:213], v[6:9]
	v_mfma_f32_16x16x32_bf16 v[2:5], v[178:181], v[210:213], v[2:5]
	s_setprio 0
	s_barrier
	s_add_i32 s58, s58, 2
	s_add_u32 s28, s28, 0x100
	s_addc_u32 s29, s29, 0
	s_add_u32 s56, s56, 0x100
	s_addc_u32 s57, s57, 0
	s_cmp_gt_u32 s58, 13
	s_cbranch_scc0 .LBB0_716
	s_and_b64 vcc, exec, s[6:7]
	s_cbranch_vccz .LBB0_719
	s_barrier

; #define PG8_STAGE(bufoff, gbase, voff) do { _Pragma("unroll") for (int _i = 0; _i < 2; ++_i) \
;         __builtin_amdgcn_global_load_lds((const unsigned*)((const char*)(gbase) + (voff)[_i]), (LAS unsigned*)(lds + (bufoff) + ldsw + _i * 8192), 16, 0, 0); } while (0)
; #define PG8_LDA(dst, b, h) do { _Pragma("unroll") for (int m = 0; m < 4; ++m) _Pragma("unroll") for (int k = 0; k < 2; ++k) dst[m][k] = *(const LAS bf16x8*)(lds + PG8_SA(b, h) + aoff + m * 2048 + k * 1024); } while (0)
; #define PG8_LDB(dst, b, h) do { _Pragma("unroll") for (int n = 0; n < 2; ++n) _Pragma("unroll") for (int k = 0; k < 2; ++k) dst[n][k] = *(const LAS bf16x8*)(lds + PG8_SB(b, h) + boff + n * 2048 + k * 1024); } while (0)
; #define PG8_MMA(ai, bj, At, Bt) do { __builtin_amdgcn_s_setprio(1); _Pragma("unroll") for (int m = 0; m < 4; ++m) _Pragma("unroll") for (int n = 0; n < 2; ++n) _Pragma("unroll") for (int k = 0; k < 2; ++k) \
;         acc[ai][bj][m][n] = __builtin_amdgcn_mfma_f32_16x16x32_bf16(Bt[n][k], At[m][k], acc[ai][bj][m][n], 0, 0, 0); __builtin_amdgcn_s_setprio(0); } while (0)
; #define PG8_WAIT_V(n) asm volatile("s_waitcnt vmcnt(" #n ")" ::: "memory")
; #define PG8_WAIT_L(n) asm volatile("s_waitcnt lgkmcnt(" #n ")" ::: "memory")
; #define PG8_BAR __builtin_amdgcn_s_barrier()
; #define PG8_SCHED __builtin_amdgcn_sched_barrier(0)
; template <class Epi>
; __device__ __forceinline__ void gemm_phase(LAS unsigned char* lds, const Gemm g, const StaticOrder& S, const Epi& E) {
;     ...
;             PG8_LDB(B0, 0, 0); PG8_LDB(B1, 0, 1); PG8_SCHED; PG8_LDA(At, 0, 0); PG8_STAGE(PG8_SA(1, 1), a1 + hstep, voffA);
;             PG8_WAIT_V(8); PG8_WAIT_L(0); PG8_BAR; PG8_MMA(0, 0, At, B0); PG8_MMA(0, 1, At, B1); PG8_BAR; PG8_SCHED;
;             PG8_LDA(At, 0, 1); PG8_STAGE(PG8_SB(0, 0), b2, voffB); PG8_STAGE(PG8_SB(0, 1), b2 + hstep, voffB); PG8_STAGE(PG8_SA(0, 0), a2, voffA);
;             PG8_WAIT_V(8); PG8_WAIT_L(0); PG8_BAR; PG8_MMA(1, 0, At, B0); PG8_MMA(1, 1, At, B1); PG8_BAR; PG8_SCHED;
.LBB0_851:
	ds_read_b128 v[146:149], v154
	ds_read_b128 v[158:161], v154 offset:1024
	ds_read_b128 v[162:165], v154 offset:2048
	ds_read_b128 v[166:169], v154 offset:3072
	ds_read_b128 v[170:173], v155
	ds_read_b128 v[174:177], v155 offset:1024
	ds_read_b128 v[178:181], v155 offset:2048
	ds_read_b128 v[182:185], v155 offset:3072
	s_add_u32 s22, s20, 0xfffc0080
	s_addc_u32 s23, s21, -1
	s_cmp_eq_u32 s49, 12
	s_cselect_b32 s25, s13, s23
	s_cselect_b32 s24, s45, s22
	s_cselect_b32 s23, s11, s48
	s_cselect_b32 s22, s46, s47
	v_lshl_add_u64 v[218:219], s[20:21], 0, v[138:139]
	s_add_i32 m0, s19, 0xc000
	ds_read_b128 v[186:189], v156
	ds_read_b128 v[190:193], v156 offset:1024
	ds_read_b128 v[194:197], v156 offset:2048
	ds_read_b128 v[198:201], v156 offset:3072
	ds_read_b128 v[202:205], v156 offset:4096
	ds_read_b128 v[206:209], v156 offset:5120
	ds_read_b128 v[210:213], v156 offset:6144
	ds_read_b128 v[214:217], v156 offset:7168
	global_load_lds_dwordx4 v[218:219], off
	v_lshl_add_u64 v[218:219], s[20:21], 0, v[140:141]
	s_add_i32 m0, s19, 0xe000
	s_nop 0
	global_load_lds_dwordx4 v[218:219], off
	s_waitcnt vmcnt(8)
	s_waitcnt lgkmcnt(0)
	s_barrier
	s_setprio 1
	v_mfma_f32_16x16x32_bf16 v[126:129], v[146:149], v[186:189], v[126:129]
	v_mfma_f32_16x16x32_bf16 v[118:121], v[162:165], v[186:189], v[118:121]
	v_mfma_f32_16x16x32_bf16 v[110:113], v[146:149], v[194:197], v[110:113]
	v_mfma_f32_16x16x32_bf16 v[102:105], v[162:165], v[194:197], v[102:105]
	v_mfma_f32_16x16x32_bf16 v[94:97], v[146:149], v[202:205], v[94:97]
	v_mfma_f32_16x16x32_bf16 v[86:89], v[162:165], v[202:205], v[86:89]
	v_mfma_f32_16x16x32_bf16 v[78:81], v[146:149], v[210:213], v[78:81]
	v_mfma_f32_16x16x32_bf16 v[70:73], v[162:165], v[210:213], v[70:73]
	v_mfma_f32_16x16x32_bf16 v[126:129], v[158:161], v[190:193], v[126:129]
	v_mfma_f32_16x16x32_bf16 v[118:121], v[166:169], v[190:193], v[118:121]
	v_mfma_f32_16x16x32_bf16 v[110:113], v[158:161], v[198:201], v[110:113]
	v_mfma_f32_16x16x32_bf16 v[102:105], v[166:169], v[198:201], v[102:105]
	v_mfma_f32_16x16x32_bf16 v[94:97], v[158:161], v[206:209], v[94:97]
	v_mfma_f32_16x16x32_bf16 v[86:89], v[166:169], v[206:209], v[86:89]
	v_mfma_f32_16x16x32_bf16 v[78:81], v[158:161], v[214:217], v[78:81]
	v_mfma_f32_16x16x32_bf16 v[70:73], v[166:169], v[214:217], v[70:73]
	s_setprio 0
	s_setprio 1
	v_mfma_f32_16x16x32_bf16 v[122:125], v[170:173], v[186:189], v[122:125]
	v_mfma_f32_16x16x32_bf16 v[114:117], v[178:181], v[186:189], v[114:117]
	v_mfma_f32_16x16x32_bf16 v[106:109], v[170:173], v[194:197], v[106:109]
	v_mfma_f32_16x16x32_bf16 v[98:101], v[178:181], v[194:197], v[98:101]
	v_mfma_f32_16x16x32_bf16 v[90:93], v[170:173], v[202:205], v[90:93]
	v_mfma_f32_16x16x32_bf16 v[82:85], v[178:181], v[202:205], v[82:85]
	v_mfma_f32_16x16x32_bf16 v[74:77], v[170:173], v[210:213], v[74:77]
	v_mfma_f32_16x16x32_bf16 v[66:69], v[178:181], v[210:213], v[66:69]
	v_mfma_f32_16x16x32_bf16 v[122:125], v[174:177], v[190:193], v[122:125]
	v_mfma_f32_16x16x32_bf16 v[114:117], v[182:185], v[190:193], v[114:117]
	v_mfma_f32_16x16x32_bf16 v[106:109], v[174:177], v[198:201], v[106:109]
	v_mfma_f32_16x16x32_bf16 v[98:101], v[182:185], v[198:201], v[98:101]
	v_mfma_f32_16x16x32_bf16 v[90:93], v[174:177], v[206:209], v[90:93]
	v_mfma_f32_16x16x32_bf16 v[82:85], v[182:185], v[206:209], v[82:85]
	v_mfma_f32_16x16x32_bf16 v[74:77], v[174:177], v[214:217], v[74:77]
	v_mfma_f32_16x16x32_bf16 v[66:69], v[182:185], v[214:217], v[66:69]
	s_setprio 0
	s_barrier
	s_add_i32 s50, s41, s30
	v_lshl_add_u64 v[218:219], s[22:23], 0, v[134:135]
	s_mov_b32 m0, s50
	ds_read_b128 v[186:189], v156 offset:16384
	ds_read_b128 v[190:193], v156 offset:17408
	ds_read_b128 v[194:197], v156 offset:18432
	ds_read_b128 v[198:201], v156 offset:19456
	ds_read_b128 v[202:205], v156 offset:20480
	ds_read_b128 v[206:209], v156 offset:21504
	ds_read_b128 v[210:213], v156 offset:22528
	ds_read_b128 v[214:217], v156 offset:23552
	global_load_lds_dwordx4 v[218:219], off
	s_add_i32 m0, s50, 0x2000
	s_add_u32 s50, s22, 0x40000
	v_lshl_add_u64 v[220:221], s[22:23], 0, v[130:131]
	s_addc_u32 s51, s23, 0
	s_add_i32 s52, s42, s30
	global_load_lds_dwordx4 v[220:221], off
	v_lshl_add_u64 v[222:223], s[50:51], 0, v[134:135]
	s_mov_b32 m0, s52
	v_lshl_add_u64 v[224:225], s[24:25], 0, v[132:133]
	global_load_lds_dwordx4 v[222:223], off
	v_lshl_add_u64 v[222:223], s[50:51], 0, v[130:131]
	s_add_i32 m0, s52, 0x2000
	s_nop 0
	global_load_lds_dwordx4 v[222:223], off
	v_lshl_add_u64 v[222:223], s[24:25], 0, v[136:137]
	s_mov_b32 m0, s19
	s_nop 0
	global_load_lds_dwordx4 v[222:223], off
	s_mov_b32 m0, s34
	s_nop 0
	global_load_lds_dwordx4 v[224:225], off
	s_waitcnt vmcnt(8)
	s_waitcnt lgkmcnt(0)
	s_barrier
; #define PG8_STAGE(bufoff, gbase, voff) do { _Pragma("unroll") for (int _i = 0; _i < 2; ++_i) \
;         __builtin_amdgcn_global_load_lds((const unsigned*)((const char*)(gbase) + (voff)[_i]), (LAS unsigned*)(lds + (bufoff) + ldsw + _i * 8192), 16, 0, 0); } while (0)
; #define PG8_LDA(dst, b, h) do { _Pragma("unroll") for (int m = 0; m < 4; ++m) _Pragma("unroll") for (int k = 0; k < 2; ++k) dst[m][k] = *(const LAS bf16x8*)(lds + PG8_SA(b, h) + aoff + m * 2048 + k * 1024); } while (0)
; #define PG8_LDB(dst, b, h) do { _Pragma("unroll") for (int n = 0; n < 2; ++n) _Pragma("unroll") for (int k = 0; k < 2; ++k) dst[n][k] = *(const LAS bf16x8*)(lds + PG8_SB(b, h) + boff + n * 2048 + k * 1024); } while (0)
; #define PG8_MMA(ai, bj, At, Bt) do { __builtin_amdgcn_s_setprio(1); _Pragma("unroll") for (int m = 0; m < 4; ++m) _Pragma("unroll") for (int n = 0; n < 2; ++n) _Pragma("unroll") for (int k = 0; k < 2; ++k) \
;         acc[ai][bj][m][n] = __builtin_amdgcn_mfma_f32_16x16x32_bf16(Bt[n][k], At[m][k], acc[ai][bj][m][n], 0, 0, 0); __builtin_amdgcn_s_setprio(0); } while (0)
; #define PG8_WAIT_V(n) asm volatile("s_waitcnt vmcnt(" #n ")" ::: "memory")
; #define PG8_WAIT_L(n) asm volatile("s_waitcnt lgkmcnt(" #n ")" ::: "memory")
; #define PG8_BAR __builtin_amdgcn_s_barrier()
; #define PG8_SCHED __builtin_amdgcn_sched_barrier(0)
; template <class Epi>
; __device__ __forceinline__ void gemm_phase(LAS unsigned char* lds, const Gemm g, const StaticOrder& S, const Epi& E) {
;     ...
;             PG8_WAIT_V(8); PG8_WAIT_L(0); PG8_BAR; PG8_MMA(1, 0, At, B0); PG8_MMA(1, 1, At, B1); PG8_BAR; PG8_SCHED;
;             PG8_LDB(B0, 1, 0); PG8_LDB(B1, 1, 1); PG8_SCHED; PG8_LDA(At, 1, 0); PG8_STAGE(PG8_SA(0, 1), a2 + hstep, voffA);
;             PG8_WAIT_V(8); PG8_WAIT_L(0); PG8_BAR; PG8_MMA(0, 0, At, B0); PG8_MMA(0, 1, At, B1); PG8_BAR; PG8_SCHED;
;             PG8_LDA(At, 1, 1); PG8_STAGE(PG8_SB(1, 0), b3, voffB); PG8_STAGE(PG8_SB(1, 1), b3 + hstep, voffB); PG8_STAGE(PG8_SA(1, 0), a3, voffA);
	s_setprio 1
	v_mfma_f32_16x16x32_bf16 v[62:65], v[146:149], v[186:189], v[62:65]
	v_mfma_f32_16x16x32_bf16 v[54:57], v[162:165], v[186:189], v[54:57]
	v_mfma_f32_16x16x32_bf16 v[46:49], v[146:149], v[194:197], v[46:49]
	v_mfma_f32_16x16x32_bf16 v[38:41], v[162:165], v[194:197], v[38:41]
	v_mfma_f32_16x16x32_bf16 v[30:33], v[146:149], v[202:205], v[30:33]
	v_mfma_f32_16x16x32_bf16 v[22:25], v[162:165], v[202:205], v[22:25]
	v_mfma_f32_16x16x32_bf16 v[14:17], v[146:149], v[210:213], v[14:17]
	v_mfma_f32_16x16x32_bf16 v[6:9], v[162:165], v[210:213], v[6:9]
	v_mfma_f32_16x16x32_bf16 v[62:65], v[158:161], v[190:193], v[62:65]
	v_mfma_f32_16x16x32_bf16 v[54:57], v[166:169], v[190:193], v[54:57]
	v_mfma_f32_16x16x32_bf16 v[46:49], v[158:161], v[198:201], v[46:49]
	v_mfma_f32_16x16x32_bf16 v[38:41], v[166:169], v[198:201], v[38:41]
	v_mfma_f32_16x16x32_bf16 v[30:33], v[158:161], v[206:209], v[30:33]
	v_mfma_f32_16x16x32_bf16 v[22:25], v[166:169], v[206:209], v[22:25]
	v_mfma_f32_16x16x32_bf16 v[14:17], v[158:161], v[214:217], v[14:17]
	v_mfma_f32_16x16x32_bf16 v[6:9], v[166:169], v[214:217], v[6:9]
	s_setprio 0
	s_setprio 1
	v_mfma_f32_16x16x32_bf16 v[58:61], v[170:173], v[186:189], v[58:61]
	v_mfma_f32_16x16x32_bf16 v[50:53], v[178:181], v[186:189], v[50:53]
	v_mfma_f32_16x16x32_bf16 v[42:45], v[170:173], v[194:197], v[42:45]
	v_mfma_f32_16x16x32_bf16 v[34:37], v[178:181], v[194:197], v[34:37]
	v_mfma_f32_16x16x32_bf16 v[26:29], v[170:173], v[202:205], v[26:29]
	v_mfma_f32_16x16x32_bf16 v[18:21], v[178:181], v[202:205], v[18:21]
	v_mfma_f32_16x16x32_bf16 v[10:13], v[170:173], v[210:213], v[10:13]
	v_mfma_f32_16x16x32_bf16 v[2:5], v[178:181], v[210:213], v[2:5]
	v_mfma_f32_16x16x32_bf16 v[58:61], v[174:177], v[190:193], v[58:61]
	v_mfma_f32_16x16x32_bf16 v[50:53], v[182:185], v[190:193], v[50:53]
	v_mfma_f32_16x16x32_bf16 v[42:45], v[174:177], v[198:201], v[42:45]
	v_mfma_f32_16x16x32_bf16 v[34:37], v[182:185], v[198:201], v[34:37]
	v_mfma_f32_16x16x32_bf16 v[26:29], v[174:177], v[206:209], v[26:29]
	v_mfma_f32_16x16x32_bf16 v[18:21], v[182:185], v[206:209], v[18:21]
	v_mfma_f32_16x16x32_bf16 v[10:13], v[174:177], v[214:217], v[10:13]
	v_mfma_f32_16x16x32_bf16 v[2:5], v[182:185], v[214:217], v[2:5]
	s_setprio 0
	s_barrier
	s_add_i32 s50, 0, 0x18000
	v_add_u32_e32 v157, s50, v152
	s_add_i32 s51, 0, 0x1c000
	ds_read_b128 v[146:149], v157
	ds_read_b128 v[158:161], v157 offset:1024
	ds_read_b128 v[162:165], v157 offset:2048
	ds_read_b128 v[166:169], v157 offset:3072
	v_add_u32_e32 v157, s51, v152
	ds_read_b128 v[170:173], v157
	ds_read_b128 v[174:177], v157 offset:1024
	ds_read_b128 v[178:181], v157 offset:2048
	ds_read_b128 v[182:185], v157 offset:3072
	s_add_u32 s24, s24, 0x40000
	s_addc_u32 s25, s25, 0
	s_mov_b32 m0, s35
	v_lshl_add_u64 v[226:227], s[24:25], 0, v[136:137]
	ds_read_b128 v[186:189], v156 offset:32768
	ds_read_b128 v[190:193], v156 offset:33792
	ds_read_b128 v[194:197], v156 offset:34816
	ds_read_b128 v[198:201], v156 offset:35840
	ds_read_b128 v[202:205], v156 offset:36864
	ds_read_b128 v[206:209], v156 offset:37888
	ds_read_b128 v[210:213], v156 offset:38912
	ds_read_b128 v[214:217], v156 offset:39936
	global_load_lds_dwordx4 v[226:227], off
	v_lshl_add_u64 v[226:227], s[24:25], 0, v[132:133]
	s_mov_b32 m0, s36
	s_nop 0
	global_load_lds_dwordx4 v[226:227], off
	s_waitcnt vmcnt(8)
	s_waitcnt lgkmcnt(0)
	s_barrier
	s_setprio 1
	v_mfma_f32_16x16x32_bf16 v[126:129], v[146:149], v[186:189], v[126:129]
	v_mfma_f32_16x16x32_bf16 v[118:121], v[162:165], v[186:189], v[118:121]
	v_mfma_f32_16x16x32_bf16 v[110:113], v[146:149], v[194:197], v[110:113]
	v_mfma_f32_16x16x32_bf16 v[102:105], v[162:165], v[194:197], v[102:105]
	v_mfma_f32_16x16x32_bf16 v[94:97], v[146:149], v[202:205], v[94:97]
	v_mfma_f32_16x16x32_bf16 v[86:89], v[162:165], v[202:205], v[86:89]
	v_mfma_f32_16x16x32_bf16 v[78:81], v[146:149], v[210:213], v[78:81]
	v_mfma_f32_16x16x32_bf16 v[70:73], v[162:165], v[210:213], v[70:73]
	v_mfma_f32_16x16x32_bf16 v[126:129], v[158:161], v[190:193], v[126:129]
	v_mfma_f32_16x16x32_bf16 v[118:121], v[166:169], v[190:193], v[118:121]
	v_mfma_f32_16x16x32_bf16 v[110:113], v[158:161], v[198:201], v[110:113]
	v_mfma_f32_16x16x32_bf16 v[102:105], v[166:169], v[198:201], v[102:105]
	v_mfma_f32_16x16x32_bf16 v[94:97], v[158:161], v[206:209], v[94:97]
	v_mfma_f32_16x16x32_bf16 v[86:89], v[166:169], v[206:209], v[86:89]
	v_mfma_f32_16x16x32_bf16 v[78:81], v[158:161], v[214:217], v[78:81]
	v_mfma_f32_16x16x32_bf16 v[70:73], v[166:169], v[214:217], v[70:73]
	s_setprio 0
	s_setprio 1
	v_mfma_f32_16x16x32_bf16 v[122:125], v[170:173], v[186:189], v[122:125]
	v_mfma_f32_16x16x32_bf16 v[114:117], v[178:181], v[186:189], v[114:117]
	v_mfma_f32_16x16x32_bf16 v[106:109], v[170:173], v[194:197], v[106:109]
	v_mfma_f32_16x16x32_bf16 v[98:101], v[178:181], v[194:197], v[98:101]
	v_mfma_f32_16x16x32_bf16 v[90:93], v[170:173], v[202:205], v[90:93]
	v_mfma_f32_16x16x32_bf16 v[82:85], v[178:181], v[202:205], v[82:85]
	v_mfma_f32_16x16x32_bf16 v[74:77], v[170:173], v[210:213], v[74:77]
	v_mfma_f32_16x16x32_bf16 v[66:69], v[178:181], v[210:213], v[66:69]
	v_mfma_f32_16x16x32_bf16 v[122:125], v[174:177], v[190:193], v[122:125]
	v_mfma_f32_16x16x32_bf16 v[114:117], v[182:185], v[190:193], v[114:117]
	v_mfma_f32_16x16x32_bf16 v[106:109], v[174:177], v[198:201], v[106:109]
	v_mfma_f32_16x16x32_bf16 v[98:101], v[182:185], v[198:201], v[98:101]
	v_mfma_f32_16x16x32_bf16 v[90:93], v[174:177], v[206:209], v[90:93]
	v_mfma_f32_16x16x32_bf16 v[82:85], v[182:185], v[206:209], v[82:85]
	v_mfma_f32_16x16x32_bf16 v[74:77], v[174:177], v[214:217], v[74:77]
	v_mfma_f32_16x16x32_bf16 v[66:69], v[182:185], v[214:217], v[66:69]
	s_setprio 0
	s_barrier
; #define PG8_STAGE(bufoff, gbase, voff) do { _Pragma("unroll") for (int _i = 0; _i < 2; ++_i) \
;         __builtin_amdgcn_global_load_lds((const unsigned*)((const char*)(gbase) + (voff)[_i]), (LAS unsigned*)(lds + (bufoff) + ldsw + _i * 8192), 16, 0, 0); } while (0)
; #define PG8_LDA(dst, b, h) do { _Pragma("unroll") for (int m = 0; m < 4; ++m) _Pragma("unroll") for (int k = 0; k < 2; ++k) dst[m][k] = *(const LAS bf16x8*)(lds + PG8_SA(b, h) + aoff + m * 2048 + k * 1024); } while (0)
; #define PG8_MMA(ai, bj, At, Bt) do { __builtin_amdgcn_s_setprio(1); _Pragma("unroll") for (int m = 0; m < 4; ++m) _Pragma("unroll") for (int n = 0; n < 2; ++n) _Pragma("unroll") for (int k = 0; k < 2; ++k) \
;         acc[ai][bj][m][n] = __builtin_amdgcn_mfma_f32_16x16x32_bf16(Bt[n][k], At[m][k], acc[ai][bj][m][n], 0, 0, 0); __builtin_amdgcn_s_setprio(0); } while (0)
; #define PG8_WAIT_V(n) asm volatile("s_waitcnt vmcnt(" #n ")" ::: "memory")
; #define PG8_WAIT_L(n) asm volatile("s_waitcnt lgkmcnt(" #n ")" ::: "memory")
; #define PG8_BAR __builtin_amdgcn_s_barrier()
; #define PG8_SCHED __builtin_amdgcn_sched_barrier(0)
; template <class Epi>
; __device__ __forceinline__ void gemm_phase(LAS unsigned char* lds, const Gemm g, const StaticOrder& S, const Epi& E) {
;     ...
;             PG8_LDA(At, 1, 1); PG8_STAGE(PG8_SB(1, 0), b3, voffB); PG8_STAGE(PG8_SB(1, 1), b3 + hstep, voffB); PG8_STAGE(PG8_SA(1, 0), a3, voffA);
;             PG8_WAIT_V(8); PG8_WAIT_L(0); PG8_BAR; PG8_MMA(1, 0, At, B0); PG8_MMA(1, 1, At, B1); PG8_BAR; PG8_SCHED;
;         }
	s_add_i32 s24, s50, s30
	v_lshl_add_u64 v[218:219], v[218:219], 0, s[6:7]
	s_mov_b32 m0, s24
	ds_read_b128 v[186:189], v156 offset:49152
	ds_read_b128 v[190:193], v156 offset:50176
	ds_read_b128 v[194:197], v156 offset:51200
	ds_read_b128 v[198:201], v156 offset:52224
	ds_read_b128 v[202:205], v156 offset:53248
	ds_read_b128 v[206:209], v156 offset:54272
	ds_read_b128 v[210:213], v156 offset:55296
	ds_read_b128 v[214:217], v156 offset:56320
	global_load_lds_dwordx4 v[218:219], off
	s_add_i32 m0, s24, 0x2000
	s_add_u32 s22, s22, 0x40080
	v_lshl_add_u64 v[218:219], v[220:221], 0, s[6:7]
	s_addc_u32 s23, s23, 0
	s_add_i32 s24, s51, s30
	global_load_lds_dwordx4 v[218:219], off
	v_lshl_add_u64 v[218:219], s[22:23], 0, v[134:135]
	s_mov_b32 m0, s24
	s_nop 0
	global_load_lds_dwordx4 v[218:219], off
	v_lshl_add_u64 v[218:219], s[22:23], 0, v[130:131]
	s_add_i32 m0, s24, 0x2000
	s_nop 0
	global_load_lds_dwordx4 v[218:219], off
	v_lshl_add_u64 v[218:219], v[222:223], 0, s[6:7]
	s_mov_b32 m0, s38
	s_nop 0
	global_load_lds_dwordx4 v[218:219], off
	v_lshl_add_u64 v[218:219], v[224:225], 0, s[6:7]
	s_mov_b32 m0, s39
	s_nop 0
	global_load_lds_dwordx4 v[218:219], off
	s_waitcnt vmcnt(8)
	s_waitcnt lgkmcnt(0)
	s_barrier
	s_setprio 1
	v_mfma_f32_16x16x32_bf16 v[62:65], v[146:149], v[186:189], v[62:65]
	v_mfma_f32_16x16x32_bf16 v[54:57], v[162:165], v[186:189], v[54:57]
	v_mfma_f32_16x16x32_bf16 v[46:49], v[146:149], v[194:197], v[46:49]
	v_mfma_f32_16x16x32_bf16 v[38:41], v[162:165], v[194:197], v[38:41]
	v_mfma_f32_16x16x32_bf16 v[30:33], v[146:149], v[202:205], v[30:33]
	v_mfma_f32_16x16x32_bf16 v[22:25], v[162:165], v[202:205], v[22:25]
	v_mfma_f32_16x16x32_bf16 v[14:17], v[146:149], v[210:213], v[14:17]
	v_mfma_f32_16x16x32_bf16 v[6:9], v[162:165], v[210:213], v[6:9]
	v_mfma_f32_16x16x32_bf16 v[62:65], v[158:161], v[190:193], v[62:65]
	v_mfma_f32_16x16x32_bf16 v[54:57], v[166:169], v[190:193], v[54:57]
	v_mfma_f32_16x16x32_bf16 v[46:49], v[158:161], v[198:201], v[46:49]
	v_mfma_f32_16x16x32_bf16 v[38:41], v[166:169], v[198:201], v[38:41]
	v_mfma_f32_16x16x32_bf16 v[30:33], v[158:161], v[206:209], v[30:33]
	v_mfma_f32_16x16x32_bf16 v[22:25], v[166:169], v[206:209], v[22:25]
	v_mfma_f32_16x16x32_bf16 v[14:17], v[158:161], v[214:217], v[14:17]
	v_mfma_f32_16x16x32_bf16 v[6:9], v[166:169], v[214:217], v[6:9]
	s_setprio 0
	s_setprio 1
	v_mfma_f32_16x16x32_bf16 v[58:61], v[170:173], v[186:189], v[58:61]
	v_mfma_f32_16x16x32_bf16 v[50:53], v[178:181], v[186:189], v[50:53]
	v_mfma_f32_16x16x32_bf16 v[42:45], v[170:173], v[194:197], v[42:45]
	v_mfma_f32_16x16x32_bf16 v[34:37], v[178:181], v[194:197], v[34:37]
	v_mfma_f32_16x16x32_bf16 v[26:29], v[170:173], v[202:205], v[26:29]
	v_mfma_f32_16x16x32_bf16 v[18:21], v[178:181], v[202:205], v[18:21]
	v_mfma_f32_16x16x32_bf16 v[10:13], v[170:173], v[210:213], v[10:13]
	v_mfma_f32_16x16x32_bf16 v[2:5], v[178:181], v[210:213], v[2:5]
	v_mfma_f32_16x16x32_bf16 v[58:61], v[174:177], v[190:193], v[58:61]
	v_mfma_f32_16x16x32_bf16 v[50:53], v[182:185], v[190:193], v[50:53]
	v_mfma_f32_16x16x32_bf16 v[42:45], v[174:177], v[198:201], v[42:45]
	v_mfma_f32_16x16x32_bf16 v[34:37], v[182:185], v[198:201], v[34:37]
	v_mfma_f32_16x16x32_bf16 v[26:29], v[174:177], v[206:209], v[26:29]
	v_mfma_f32_16x16x32_bf16 v[18:21], v[182:185], v[206:209], v[18:21]
	v_mfma_f32_16x16x32_bf16 v[10:13], v[174:177], v[214:217], v[10:13]
	v_mfma_f32_16x16x32_bf16 v[2:5], v[182:185], v[214:217], v[2:5]
	s_setprio 0
	s_barrier
	s_add_i32 s49, s49, 2
	s_add_u32 s20, s20, 0x100
	s_addc_u32 s21, s21, 0
	s_add_u32 s47, s47, 0x100
	s_addc_u32 s48, s48, 0
	s_cmp_gt_u32 s49, 13
	s_cbranch_scc0 .LBB0_851
	s_and_b64 vcc, exec, s[8:9]
	s_cbranch_vccz .LBB0_854
	s_barrier

; #define PG8_STAGE(bufoff, gbase, voff) do { _Pragma("unroll") for (int _i = 0; _i < 2; ++_i) \
;         __builtin_amdgcn_global_load_lds((const unsigned*)((const char*)(gbase) + (voff)[_i]), (LAS unsigned*)(lds + (bufoff) + ldsw + _i * 8192), 16, 0, 0); } while (0)
; #define PG8_LDA(dst, b, h) do { _Pragma("unroll") for (int m = 0; m < 4; ++m) _Pragma("unroll") for (int k = 0; k < 2; ++k) dst[m][k] = *(const LAS bf16x8*)(lds + PG8_SA(b, h) + aoff + m * 2048 + k * 1024); } while (0)
; #define PG8_LDB(dst, b, h) do { _Pragma("unroll") for (int n = 0; n < 2; ++n) _Pragma("unroll") for (int k = 0; k < 2; ++k) dst[n][k] = *(const LAS bf16x8*)(lds + PG8_SB(b, h) + boff + n * 2048 + k * 1024); } while (0)
; #define PG8_MMA(ai, bj, At, Bt) do { __builtin_amdgcn_s_setprio(1); _Pragma("unroll") for (int m = 0; m < 4; ++m) _Pragma("unroll") for (int n = 0; n < 2; ++n) _Pragma("unroll") for (int k = 0; k < 2; ++k) \
;         acc[ai][bj][m][n] = __builtin_amdgcn_mfma_f32_16x16x32_bf16(Bt[n][k], At[m][k], acc[ai][bj][m][n], 0, 0, 0); __builtin_amdgcn_s_setprio(0); } while (0)
; #define PG8_WAIT_V(n) asm volatile("s_waitcnt vmcnt(" #n ")" ::: "memory")
; #define PG8_WAIT_L(n) asm volatile("s_waitcnt lgkmcnt(" #n ")" ::: "memory")
; #define PG8_BAR __builtin_amdgcn_s_barrier()
; #define PG8_SCHED __builtin_amdgcn_sched_barrier(0)
; template <class Epi>
; __device__ __forceinline__ void gemm_phase(LAS unsigned char* lds, const Gemm g, const StaticOrder& S, const Epi& E) {
;     ...
;             PG8_LDB(B0, 0, 0); PG8_LDB(B1, 0, 1); PG8_SCHED; PG8_LDA(At, 0, 0); PG8_STAGE(PG8_SA(1, 1), a1 + hstep, voffA);
;             PG8_WAIT_V(8); PG8_WAIT_L(0); PG8_BAR; PG8_MMA(0, 0, At, B0); PG8_MMA(0, 1, At, B1); PG8_BAR; PG8_SCHED;
;             PG8_LDA(At, 0, 1); PG8_STAGE(PG8_SB(0, 0), b2, voffB); PG8_STAGE(PG8_SB(0, 1), b2 + hstep, voffB); PG8_STAGE(PG8_SA(0, 0), a2, voffA);
;             PG8_WAIT_V(8); PG8_WAIT_L(0); PG8_BAR; PG8_MMA(1, 0, At, B0); PG8_MMA(1, 1, At, B1); PG8_BAR; PG8_SCHED;
.LBB0_937:
	ds_read_b128 v[130:133], v196
	ds_read_b128 v[134:137], v196 offset:1024
	ds_read_b128 v[138:141], v196 offset:2048
	ds_read_b128 v[142:145], v196 offset:3072
	ds_read_b128 v[146:149], v197
	ds_read_b128 v[150:153], v197 offset:1024
	ds_read_b128 v[154:157], v197 offset:2048
	ds_read_b128 v[158:161], v197 offset:3072
	s_add_u32 s24, s22, 0xfff50080
	s_addc_u32 s25, s23, -1
	s_cmp_eq_u32 s54, 40
	s_cselect_b32 s27, s5, s25
	s_cselect_b32 s26, s4, s24
	s_cselect_b32 s25, s21, s53
	s_cselect_b32 s24, s20, s52
	v_lshl_add_u64 v[190:191], s[22:23], 0, v[174:175]
	s_add_i32 m0, s34, 0xc000
	ds_read_b128 v[162:165], v198
	ds_read_b128 v[166:169], v198 offset:1024
	ds_read_b128 v[182:185], v198 offset:2048
	ds_read_b128 v[186:189], v198 offset:3072
	ds_read_b128 v[200:203], v198 offset:4096
	ds_read_b128 v[204:207], v198 offset:5120
	ds_read_b128 v[208:211], v198 offset:6144
	ds_read_b128 v[212:215], v198 offset:7168
	global_load_lds_dwordx4 v[190:191], off
	v_lshl_add_u64 v[190:191], s[22:23], 0, v[176:177]
	s_add_i32 m0, s34, 0xe000
	s_nop 0
	global_load_lds_dwordx4 v[190:191], off
	s_waitcnt vmcnt(8)
	s_waitcnt lgkmcnt(0)
	s_barrier
	s_setprio 1
	v_mfma_f32_16x16x32_bf16 v[126:129], v[130:133], v[162:165], v[126:129]
	v_mfma_f32_16x16x32_bf16 v[122:125], v[138:141], v[162:165], v[122:125]
	v_mfma_f32_16x16x32_bf16 v[118:121], v[130:133], v[182:185], v[118:121]
	v_mfma_f32_16x16x32_bf16 v[114:117], v[138:141], v[182:185], v[114:117]
	v_mfma_f32_16x16x32_bf16 v[94:97], v[130:133], v[200:203], v[94:97]
	v_mfma_f32_16x16x32_bf16 v[90:93], v[138:141], v[200:203], v[90:93]
	v_mfma_f32_16x16x32_bf16 v[82:85], v[130:133], v[208:211], v[82:85]
	v_mfma_f32_16x16x32_bf16 v[74:77], v[138:141], v[208:211], v[74:77]
	v_mfma_f32_16x16x32_bf16 v[126:129], v[134:137], v[166:169], v[126:129]
	v_mfma_f32_16x16x32_bf16 v[122:125], v[142:145], v[166:169], v[122:125]
	v_mfma_f32_16x16x32_bf16 v[118:121], v[134:137], v[186:189], v[118:121]
	v_mfma_f32_16x16x32_bf16 v[114:117], v[142:145], v[186:189], v[114:117]
	v_mfma_f32_16x16x32_bf16 v[94:97], v[134:137], v[204:207], v[94:97]
	v_mfma_f32_16x16x32_bf16 v[90:93], v[142:145], v[204:207], v[90:93]
	v_mfma_f32_16x16x32_bf16 v[82:85], v[134:137], v[212:215], v[82:85]
	v_mfma_f32_16x16x32_bf16 v[74:77], v[142:145], v[212:215], v[74:77]
	s_setprio 0
	s_setprio 1
	v_mfma_f32_16x16x32_bf16 v[110:113], v[146:149], v[162:165], v[110:113]
	v_mfma_f32_16x16x32_bf16 v[106:109], v[154:157], v[162:165], v[106:109]
	v_mfma_f32_16x16x32_bf16 v[102:105], v[146:149], v[182:185], v[102:105]
	v_mfma_f32_16x16x32_bf16 v[98:101], v[154:157], v[182:185], v[98:101]
	v_mfma_f32_16x16x32_bf16 v[86:89], v[146:149], v[200:203], v[86:89]
	v_mfma_f32_16x16x32_bf16 v[78:81], v[154:157], v[200:203], v[78:81]
	v_mfma_f32_16x16x32_bf16 v[70:73], v[146:149], v[208:211], v[70:73]
	v_mfma_f32_16x16x32_bf16 v[66:69], v[154:157], v[208:211], v[66:69]
	v_mfma_f32_16x16x32_bf16 v[110:113], v[150:153], v[166:169], v[110:113]
	v_mfma_f32_16x16x32_bf16 v[106:109], v[158:161], v[166:169], v[106:109]
	v_mfma_f32_16x16x32_bf16 v[102:105], v[150:153], v[186:189], v[102:105]
	v_mfma_f32_16x16x32_bf16 v[98:101], v[158:161], v[186:189], v[98:101]
	v_mfma_f32_16x16x32_bf16 v[86:89], v[150:153], v[204:207], v[86:89]
	v_mfma_f32_16x16x32_bf16 v[78:81], v[158:161], v[204:207], v[78:81]
	v_mfma_f32_16x16x32_bf16 v[70:73], v[150:153], v[212:215], v[70:73]
	v_mfma_f32_16x16x32_bf16 v[66:69], v[158:161], v[212:215], v[66:69]
	s_setprio 0
	s_barrier
	s_add_i32 s55, s42, s33
	v_lshl_add_u64 v[190:191], s[24:25], 0, v[170:171]
	s_mov_b32 m0, s55
	ds_read_b128 v[162:165], v198 offset:16384
	ds_read_b128 v[166:169], v198 offset:17408
	ds_read_b128 v[182:185], v198 offset:18432
	ds_read_b128 v[186:189], v198 offset:19456
	ds_read_b128 v[200:203], v198 offset:20480
	ds_read_b128 v[204:207], v198 offset:21504
	ds_read_b128 v[208:211], v198 offset:22528
	ds_read_b128 v[212:215], v198 offset:23552
	global_load_lds_dwordx4 v[190:191], off
	s_add_i32 m0, s55, 0x2000
	s_add_u32 s56, s24, 0xb0000
	v_lshl_add_u64 v[216:217], s[24:25], 0, v[172:173]
	s_addc_u32 s57, s25, 0
	s_add_i32 s55, s43, s33
	global_load_lds_dwordx4 v[216:217], off
	v_lshl_add_u64 v[218:219], s[56:57], 0, v[170:171]
	s_mov_b32 m0, s55
	v_lshl_add_u64 v[220:221], s[26:27], 0, v[172:173]
	global_load_lds_dwordx4 v[218:219], off
	v_lshl_add_u64 v[218:219], s[56:57], 0, v[172:173]
	s_add_i32 m0, s55, 0x2000
	s_nop 0
	global_load_lds_dwordx4 v[218:219], off
	v_lshl_add_u64 v[218:219], s[26:27], 0, v[170:171]
	s_mov_b32 m0, s34
	s_nop 0
	global_load_lds_dwordx4 v[218:219], off
	s_mov_b32 m0, s35
	s_nop 0
	global_load_lds_dwordx4 v[220:221], off
	s_waitcnt vmcnt(8)
	s_waitcnt lgkmcnt(0)
	s_barrier
; #define PG8_STAGE(bufoff, gbase, voff) do { _Pragma("unroll") for (int _i = 0; _i < 2; ++_i) \
;         __builtin_amdgcn_global_load_lds((const unsigned*)((const char*)(gbase) + (voff)[_i]), (LAS unsigned*)(lds + (bufoff) + ldsw + _i * 8192), 16, 0, 0); } while (0)
; #define PG8_LDA(dst, b, h) do { _Pragma("unroll") for (int m = 0; m < 4; ++m) _Pragma("unroll") for (int k = 0; k < 2; ++k) dst[m][k] = *(const LAS bf16x8*)(lds + PG8_SA(b, h) + aoff + m * 2048 + k * 1024); } while (0)
; #define PG8_LDB(dst, b, h) do { _Pragma("unroll") for (int n = 0; n < 2; ++n) _Pragma("unroll") for (int k = 0; k < 2; ++k) dst[n][k] = *(const LAS bf16x8*)(lds + PG8_SB(b, h) + boff + n * 2048 + k * 1024); } while (0)
; #define PG8_MMA(ai, bj, At, Bt) do { __builtin_amdgcn_s_setprio(1); _Pragma("unroll") for (int m = 0; m < 4; ++m) _Pragma("unroll") for (int n = 0; n < 2; ++n) _Pragma("unroll") for (int k = 0; k < 2; ++k) \
;         acc[ai][bj][m][n] = __builtin_amdgcn_mfma_f32_16x16x32_bf16(Bt[n][k], At[m][k], acc[ai][bj][m][n], 0, 0, 0); __builtin_amdgcn_s_setprio(0); } while (0)
; #define PG8_WAIT_V(n) asm volatile("s_waitcnt vmcnt(" #n ")" ::: "memory")
; #define PG8_WAIT_L(n) asm volatile("s_waitcnt lgkmcnt(" #n ")" ::: "memory")
; #define PG8_BAR __builtin_amdgcn_s_barrier()
; #define PG8_SCHED __builtin_amdgcn_sched_barrier(0)
; template <class Epi>
; __device__ __forceinline__ void gemm_phase(LAS unsigned char* lds, const Gemm g, const StaticOrder& S, const Epi& E) {
;     ...
;             PG8_WAIT_V(8); PG8_WAIT_L(0); PG8_BAR; PG8_MMA(1, 0, At, B0); PG8_MMA(1, 1, At, B1); PG8_BAR; PG8_SCHED;
;             PG8_LDB(B0, 1, 0); PG8_LDB(B1, 1, 1); PG8_SCHED; PG8_LDA(At, 1, 0); PG8_STAGE(PG8_SA(0, 1), a2 + hstep, voffA);
;             PG8_WAIT_V(8); PG8_WAIT_L(0); PG8_BAR; PG8_MMA(0, 0, At, B0); PG8_MMA(0, 1, At, B1); PG8_BAR; PG8_SCHED;
;             PG8_LDA(At, 1, 1); PG8_STAGE(PG8_SB(1, 0), b3, voffB); PG8_STAGE(PG8_SB(1, 1), b3 + hstep, voffB); PG8_STAGE(PG8_SA(1, 0), a3, voffA);
	s_setprio 1
	v_mfma_f32_16x16x32_bf16 v[62:65], v[130:133], v[162:165], v[62:65]
	v_mfma_f32_16x16x32_bf16 v[58:61], v[138:141], v[162:165], v[58:61]
	v_mfma_f32_16x16x32_bf16 v[54:57], v[130:133], v[182:185], v[54:57]
	v_mfma_f32_16x16x32_bf16 v[50:53], v[138:141], v[182:185], v[50:53]
	v_mfma_f32_16x16x32_bf16 v[38:41], v[130:133], v[200:203], v[38:41]
	v_mfma_f32_16x16x32_bf16 v[34:37], v[138:141], v[200:203], v[34:37]
	v_mfma_f32_16x16x32_bf16 v[22:25], v[130:133], v[208:211], v[22:25]
	v_mfma_f32_16x16x32_bf16 v[18:21], v[138:141], v[208:211], v[18:21]
	v_mfma_f32_16x16x32_bf16 v[62:65], v[134:137], v[166:169], v[62:65]
	v_mfma_f32_16x16x32_bf16 v[58:61], v[142:145], v[166:169], v[58:61]
	v_mfma_f32_16x16x32_bf16 v[54:57], v[134:137], v[186:189], v[54:57]
	v_mfma_f32_16x16x32_bf16 v[50:53], v[142:145], v[186:189], v[50:53]
	v_mfma_f32_16x16x32_bf16 v[38:41], v[134:137], v[204:207], v[38:41]
	v_mfma_f32_16x16x32_bf16 v[34:37], v[142:145], v[204:207], v[34:37]
	v_mfma_f32_16x16x32_bf16 v[22:25], v[134:137], v[212:215], v[22:25]
	v_mfma_f32_16x16x32_bf16 v[18:21], v[142:145], v[212:215], v[18:21]
	s_setprio 0
	s_setprio 1
	v_mfma_f32_16x16x32_bf16 v[46:49], v[146:149], v[162:165], v[46:49]
	v_mfma_f32_16x16x32_bf16 v[42:45], v[154:157], v[162:165], v[42:45]
	v_mfma_f32_16x16x32_bf16 v[30:33], v[146:149], v[182:185], v[30:33]
	v_mfma_f32_16x16x32_bf16 v[26:29], v[154:157], v[182:185], v[26:29]
	v_mfma_f32_16x16x32_bf16 v[14:17], v[146:149], v[200:203], v[14:17]
	v_mfma_f32_16x16x32_bf16 v[10:13], v[154:157], v[200:203], v[10:13]
	v_mfma_f32_16x16x32_bf16 v[6:9], v[146:149], v[208:211], v[6:9]
	v_mfma_f32_16x16x32_bf16 v[2:5], v[154:157], v[208:211], v[2:5]
	v_mfma_f32_16x16x32_bf16 v[46:49], v[150:153], v[166:169], v[46:49]
	v_mfma_f32_16x16x32_bf16 v[42:45], v[158:161], v[166:169], v[42:45]
	v_mfma_f32_16x16x32_bf16 v[30:33], v[150:153], v[186:189], v[30:33]
	v_mfma_f32_16x16x32_bf16 v[26:29], v[158:161], v[186:189], v[26:29]
	v_mfma_f32_16x16x32_bf16 v[14:17], v[150:153], v[204:207], v[14:17]
	v_mfma_f32_16x16x32_bf16 v[10:13], v[158:161], v[204:207], v[10:13]
	v_mfma_f32_16x16x32_bf16 v[6:9], v[150:153], v[212:215], v[6:9]
	v_mfma_f32_16x16x32_bf16 v[2:5], v[158:161], v[212:215], v[2:5]
	s_setprio 0
	s_barrier
	s_add_i32 s55, 0, 0x18000
	s_add_i32 s56, 0, 0x1c000
	v_add_u32_e32 v142, s55, v194
	v_add_u32_e32 v158, s56, v194
	ds_read_b128 v[130:133], v142
	ds_read_b128 v[134:137], v142 offset:1024
	ds_read_b128 v[138:141], v142 offset:2048
	ds_read_b128 v[142:145], v142 offset:3072
	ds_read_b128 v[146:149], v158
	ds_read_b128 v[150:153], v158 offset:1024
	ds_read_b128 v[154:157], v158 offset:2048
	ds_read_b128 v[158:161], v158 offset:3072
	s_add_u32 s26, s26, 0xb0000
	s_addc_u32 s27, s27, 0
	s_mov_b32 m0, s36
	v_lshl_add_u64 v[222:223], s[26:27], 0, v[170:171]
	ds_read_b128 v[162:165], v198 offset:32768
	ds_read_b128 v[166:169], v198 offset:33792
	ds_read_b128 v[182:185], v198 offset:34816
	ds_read_b128 v[186:189], v198 offset:35840
	ds_read_b128 v[200:203], v198 offset:36864
	ds_read_b128 v[204:207], v198 offset:37888
	ds_read_b128 v[208:211], v198 offset:38912
	ds_read_b128 v[212:215], v198 offset:39936
	global_load_lds_dwordx4 v[222:223], off
	v_lshl_add_u64 v[222:223], s[26:27], 0, v[172:173]
	s_mov_b32 m0, s37
	s_nop 0
	global_load_lds_dwordx4 v[222:223], off
	s_waitcnt vmcnt(8)
	s_waitcnt lgkmcnt(0)
	s_barrier
	s_setprio 1
	v_mfma_f32_16x16x32_bf16 v[126:129], v[130:133], v[162:165], v[126:129]
	v_mfma_f32_16x16x32_bf16 v[122:125], v[138:141], v[162:165], v[122:125]
	v_mfma_f32_16x16x32_bf16 v[118:121], v[130:133], v[182:185], v[118:121]
	v_mfma_f32_16x16x32_bf16 v[114:117], v[138:141], v[182:185], v[114:117]
	v_mfma_f32_16x16x32_bf16 v[94:97], v[130:133], v[200:203], v[94:97]
	v_mfma_f32_16x16x32_bf16 v[90:93], v[138:141], v[200:203], v[90:93]
	v_mfma_f32_16x16x32_bf16 v[82:85], v[130:133], v[208:211], v[82:85]
	v_mfma_f32_16x16x32_bf16 v[74:77], v[138:141], v[208:211], v[74:77]
	v_mfma_f32_16x16x32_bf16 v[126:129], v[134:137], v[166:169], v[126:129]
	v_mfma_f32_16x16x32_bf16 v[122:125], v[142:145], v[166:169], v[122:125]
	v_mfma_f32_16x16x32_bf16 v[118:121], v[134:137], v[186:189], v[118:121]
	v_mfma_f32_16x16x32_bf16 v[114:117], v[142:145], v[186:189], v[114:117]
	v_mfma_f32_16x16x32_bf16 v[94:97], v[134:137], v[204:207], v[94:97]
	v_mfma_f32_16x16x32_bf16 v[90:93], v[142:145], v[204:207], v[90:93]
	v_mfma_f32_16x16x32_bf16 v[82:85], v[134:137], v[212:215], v[82:85]
	v_mfma_f32_16x16x32_bf16 v[74:77], v[142:145], v[212:215], v[74:77]
	s_setprio 0
	s_setprio 1
	v_mfma_f32_16x16x32_bf16 v[110:113], v[146:149], v[162:165], v[110:113]
	v_mfma_f32_16x16x32_bf16 v[106:109], v[154:157], v[162:165], v[106:109]
	v_mfma_f32_16x16x32_bf16 v[102:105], v[146:149], v[182:185], v[102:105]
	v_mfma_f32_16x16x32_bf16 v[98:101], v[154:157], v[182:185], v[98:101]
	v_mfma_f32_16x16x32_bf16 v[86:89], v[146:149], v[200:203], v[86:89]
	v_mfma_f32_16x16x32_bf16 v[78:81], v[154:157], v[200:203], v[78:81]
	v_mfma_f32_16x16x32_bf16 v[70:73], v[146:149], v[208:211], v[70:73]
	v_mfma_f32_16x16x32_bf16 v[66:69], v[154:157], v[208:211], v[66:69]
	v_mfma_f32_16x16x32_bf16 v[110:113], v[150:153], v[166:169], v[110:113]
	v_mfma_f32_16x16x32_bf16 v[106:109], v[158:161], v[166:169], v[106:109]
	v_mfma_f32_16x16x32_bf16 v[102:105], v[150:153], v[186:189], v[102:105]
	v_mfma_f32_16x16x32_bf16 v[98:101], v[158:161], v[186:189], v[98:101]
	v_mfma_f32_16x16x32_bf16 v[86:89], v[150:153], v[204:207], v[86:89]
	v_mfma_f32_16x16x32_bf16 v[78:81], v[158:161], v[204:207], v[78:81]
	v_mfma_f32_16x16x32_bf16 v[70:73], v[150:153], v[212:215], v[70:73]
	v_mfma_f32_16x16x32_bf16 v[66:69], v[158:161], v[212:215], v[66:69]
	s_setprio 0
	s_barrier
; #define PG8_STAGE(bufoff, gbase, voff) do { _Pragma("unroll") for (int _i = 0; _i < 2; ++_i) \
;         __builtin_amdgcn_global_load_lds((const unsigned*)((const char*)(gbase) + (voff)[_i]), (LAS unsigned*)(lds + (bufoff) + ldsw + _i * 8192), 16, 0, 0); } while (0)
; #define PG8_LDA(dst, b, h) do { _Pragma("unroll") for (int m = 0; m < 4; ++m) _Pragma("unroll") for (int k = 0; k < 2; ++k) dst[m][k] = *(const LAS bf16x8*)(lds + PG8_SA(b, h) + aoff + m * 2048 + k * 1024); } while (0)
; #define PG8_MMA(ai, bj, At, Bt) do { __builtin_amdgcn_s_setprio(1); _Pragma("unroll") for (int m = 0; m < 4; ++m) _Pragma("unroll") for (int n = 0; n < 2; ++n) _Pragma("unroll") for (int k = 0; k < 2; ++k) \
;         acc[ai][bj][m][n] = __builtin_amdgcn_mfma_f32_16x16x32_bf16(Bt[n][k], At[m][k], acc[ai][bj][m][n], 0, 0, 0); __builtin_amdgcn_s_setprio(0); } while (0)
; #define PG8_WAIT_V(n) asm volatile("s_waitcnt vmcnt(" #n ")" ::: "memory")
; #define PG8_WAIT_L(n) asm volatile("s_waitcnt lgkmcnt(" #n ")" ::: "memory")
; #define PG8_BAR __builtin_amdgcn_s_barrier()
; #define PG8_SCHED __builtin_amdgcn_sched_barrier(0)
; template <class Epi>
; __device__ __forceinline__ void gemm_phase(LAS unsigned char* lds, const Gemm g, const StaticOrder& S, const Epi& E) {
;     ...
;             PG8_LDA(At, 1, 1); PG8_STAGE(PG8_SB(1, 0), b3, voffB); PG8_STAGE(PG8_SB(1, 1), b3 + hstep, voffB); PG8_STAGE(PG8_SA(1, 0), a3, voffA);
;             PG8_WAIT_V(8); PG8_WAIT_L(0); PG8_BAR; PG8_MMA(1, 0, At, B0); PG8_MMA(1, 1, At, B1); PG8_BAR; PG8_SCHED;
;         }
	s_add_i32 s26, s55, s33
	v_lshl_add_u64 v[190:191], v[190:191], 0, s[8:9]
	s_mov_b32 m0, s26
	ds_read_b128 v[162:165], v198 offset:49152
	ds_read_b128 v[166:169], v198 offset:50176
	ds_read_b128 v[182:185], v198 offset:51200
	ds_read_b128 v[186:189], v198 offset:52224
	ds_read_b128 v[200:203], v198 offset:53248
	ds_read_b128 v[204:207], v198 offset:54272
	ds_read_b128 v[208:211], v198 offset:55296
	ds_read_b128 v[212:215], v198 offset:56320
	global_load_lds_dwordx4 v[190:191], off
	s_add_i32 m0, s26, 0x2000
	s_add_u32 s24, s24, 0xb0080
	v_lshl_add_u64 v[190:191], v[216:217], 0, s[8:9]
	s_addc_u32 s25, s25, 0
	s_add_i32 s26, s56, s33
	global_load_lds_dwordx4 v[190:191], off
	v_lshl_add_u64 v[190:191], s[24:25], 0, v[170:171]
	s_mov_b32 m0, s26
	s_nop 0
	global_load_lds_dwordx4 v[190:191], off
	v_lshl_add_u64 v[190:191], s[24:25], 0, v[172:173]
	s_add_i32 m0, s26, 0x2000
	s_nop 0
	global_load_lds_dwordx4 v[190:191], off
	v_lshl_add_u64 v[190:191], v[218:219], 0, s[8:9]
	s_mov_b32 m0, s39
	s_nop 0
	global_load_lds_dwordx4 v[190:191], off
	v_lshl_add_u64 v[190:191], v[220:221], 0, s[8:9]
	s_mov_b32 m0, s40
	s_nop 0
	global_load_lds_dwordx4 v[190:191], off
	s_waitcnt vmcnt(8)
	s_waitcnt lgkmcnt(0)
	s_barrier
	s_setprio 1
	v_mfma_f32_16x16x32_bf16 v[62:65], v[130:133], v[162:165], v[62:65]
	v_mfma_f32_16x16x32_bf16 v[58:61], v[138:141], v[162:165], v[58:61]
	v_mfma_f32_16x16x32_bf16 v[54:57], v[130:133], v[182:185], v[54:57]
	v_mfma_f32_16x16x32_bf16 v[50:53], v[138:141], v[182:185], v[50:53]
	v_mfma_f32_16x16x32_bf16 v[38:41], v[130:133], v[200:203], v[38:41]
	v_mfma_f32_16x16x32_bf16 v[34:37], v[138:141], v[200:203], v[34:37]
	v_mfma_f32_16x16x32_bf16 v[22:25], v[130:133], v[208:211], v[22:25]
	v_mfma_f32_16x16x32_bf16 v[18:21], v[138:141], v[208:211], v[18:21]
	v_mfma_f32_16x16x32_bf16 v[62:65], v[134:137], v[166:169], v[62:65]
	v_mfma_f32_16x16x32_bf16 v[58:61], v[142:145], v[166:169], v[58:61]
	v_mfma_f32_16x16x32_bf16 v[54:57], v[134:137], v[186:189], v[54:57]
	v_mfma_f32_16x16x32_bf16 v[50:53], v[142:145], v[186:189], v[50:53]
	v_mfma_f32_16x16x32_bf16 v[38:41], v[134:137], v[204:207], v[38:41]
	v_mfma_f32_16x16x32_bf16 v[34:37], v[142:145], v[204:207], v[34:37]
	v_mfma_f32_16x16x32_bf16 v[22:25], v[134:137], v[212:215], v[22:25]
	v_mfma_f32_16x16x32_bf16 v[18:21], v[142:145], v[212:215], v[18:21]
	s_setprio 0
	s_setprio 1
	v_mfma_f32_16x16x32_bf16 v[46:49], v[146:149], v[162:165], v[46:49]
	v_mfma_f32_16x16x32_bf16 v[42:45], v[154:157], v[162:165], v[42:45]
	v_mfma_f32_16x16x32_bf16 v[30:33], v[146:149], v[182:185], v[30:33]
	v_mfma_f32_16x16x32_bf16 v[26:29], v[154:157], v[182:185], v[26:29]
	v_mfma_f32_16x16x32_bf16 v[14:17], v[146:149], v[200:203], v[14:17]
	v_mfma_f32_16x16x32_bf16 v[10:13], v[154:157], v[200:203], v[10:13]
	v_mfma_f32_16x16x32_bf16 v[6:9], v[146:149], v[208:211], v[6:9]
	v_mfma_f32_16x16x32_bf16 v[2:5], v[154:157], v[208:211], v[2:5]
	v_mfma_f32_16x16x32_bf16 v[46:49], v[150:153], v[166:169], v[46:49]
	v_mfma_f32_16x16x32_bf16 v[42:45], v[158:161], v[166:169], v[42:45]
	v_mfma_f32_16x16x32_bf16 v[30:33], v[150:153], v[186:189], v[30:33]
	v_mfma_f32_16x16x32_bf16 v[26:29], v[158:161], v[186:189], v[26:29]
	v_mfma_f32_16x16x32_bf16 v[14:17], v[150:153], v[204:207], v[14:17]
	v_mfma_f32_16x16x32_bf16 v[10:13], v[158:161], v[204:207], v[10:13]
	v_mfma_f32_16x16x32_bf16 v[6:9], v[150:153], v[212:215], v[6:9]
	v_mfma_f32_16x16x32_bf16 v[2:5], v[158:161], v[212:215], v[2:5]
	s_setprio 0
	s_barrier
	s_add_i32 s54, s54, 2
	s_add_u32 s22, s22, 0x100
	s_addc_u32 s23, s23, 0
	s_add_u32 s52, s52, 0x100
	s_addc_u32 s53, s53, 0
	s_cmp_gt_u32 s54, 41
	s_cbranch_scc0 .LBB0_937
	s_and_b64 vcc, exec, s[10:11]
	s_cbranch_vccz .LBB0_940
	s_barrier
